# attention: waves 0-3 and 4-7 rendezvous at different points of the tile loop (half-tile stagger), V staged one tile further ahead
# speedup vs baseline: 1.0104x; 1.0104x over previous
.LBB0_327:
	s_cmp_lt_i32 s28, 6
	s_cselect_b64 s[0:1], -1, 0
	s_cmp_gt_i32 s29, 5
	s_cselect_b64 s[4:5], -1, 0
	s_and_b64 s[4:5], s[0:1], s[4:5]
	s_andn2_b64 vcc, exec, s[4:5]
	s_cbranch_vccnz .LBB0_377
	s_cmpk_lt_u32 s65, 0x100
	s_cselect_b32 s98, 0, 1
	s_cbranch_scc1 .LBB0_330
	s_setprio 1
.LBB0_330:
	s_cmpk_gt_i32 s2, 0x7ff
	s_cbranch_scc1 .LBB0_376
	s_lshl_b32 s0, s2, 5
	s_and_b32 s0, s0, 0x400
	s_cmpk_eq_i32 s30, 0x100
	s_cselect_b32 s46, s0, 0x100
	s_add_u32 s47, s26, 0xc000000
	s_addc_u32 s70, s27, 0
	s_add_u32 s96, s26, 0x17000000
	s_addc_u32 s97, s27, 0
	s_add_u32 s40, s26, 0x11000000
	s_addc_u32 s41, s27, 0
	s_add_u32 s92, s26, 0x1a000000
	s_addc_u32 s93, s27, 0
	s_add_u32 s66, s26, 0x13000000
	s_addc_u32 s67, s27, 0
	v_writelane_b32 v242, s4, 39
	s_add_u32 s69, s26, 0x1a800000
	s_addc_u32 s10, s27, 0
	v_writelane_b32 v242, s5, 40
	v_lshrrev_b32_e32 v3, 3, v168
	v_lshlrev_b32_e32 v0, 4, v168
	v_writelane_b32 v242, s82, 37
	s_add_u32 s11, s26, 0x90000
	v_and_b32_e32 v1, 0x70, v0
	v_and_b32_e32 v5, 0x60, v0
	v_lshlrev_b32_e32 v4, 3, v168
	v_mul_u32_u24_e32 v8, 0x90, v3
	v_writelane_b32 v242, s83, 38
	s_addc_u32 s0, s27, 0
	v_and_b32_e32 v6, 8, v4
	v_add3_u32 v177, v8, v1, 0
	v_add_u32_e32 v1, 0, v5
	v_add_u32_e32 v5, 0x200, v168
	v_writelane_b32 v242, s0, 36
	v_add3_u32 v198, v1, v6, v8
	v_mul_u32_u24_e32 v6, 0x1556, v5
	v_and_b32_e32 v170, 31, v168
	v_lshrrev_b32_e32 v171, 5, v169
	v_readlane_b32 s0, v242, 33
	v_mul_u32_u24_e32 v1, 0x1556, v168
	v_lshrrev_b32_e32 v6, 16, v6
	s_lshl_b32 s14, s0, 5
	v_lshlrev_b32_e32 v7, 4, v171
	v_lshrrev_b32_e32 v1, 16, v1
	v_add_lshl_u32 v206, v5, v6, 4
	v_mul_u32_u24_e32 v5, 0xd0, v170
	v_mov_b32_e32 v173, 0
	s_add_u32 s0, s26, 0x70000
	v_add_lshl_u32 v207, v168, v1, 4
	v_add3_u32 v208, 0, v5, v7
	v_lshlrev_b32_e32 v1, 6, v170
	v_and_b32_e32 v5, 7, v168
	s_movk_i32 s1, 0x100
	v_or_b32_e32 v172, s14, v170
	v_writelane_b32 v242, s0, 33
	s_addc_u32 s0, s27, 0
	v_sub_u32_e32 v209, v208, v1
	v_mov_b32_e32 v1, v173
	v_lshlrev_b32_e32 v5, 4, v5
	v_mul_u32_u24_e32 v9, 0x90, v170
	v_lshlrev_b64 v[174:175], 11, v[172:173]
	v_writelane_b32 v242, s0, 34
	v_cmp_gt_u32_e64 s[4:5], s1, v168
	v_lshl_add_u64 v[0:1], s[26:27], 0, v[0:1]
	s_mov_b64 s[0:1], 0x1a006000
	v_lshl_or_b32 v172, v3, 16, v5
	v_add3_u32 v199, v7, v9, 0
	v_lshl_add_u64 v[178:179], v[0:1], 0, s[0:1]
	v_lshl_add_u64 v[6:7], s[26:27], 0, v[172:173]
	s_mov_b64 s[0:1], 0x13000180
	v_lshl_add_u64 v[180:181], v[6:7], 0, s[0:1]
	s_mov_b64 s[0:1], 0x1700b000
	v_cmp_gt_u32_e64 s[6:7], 32, v169
	v_exp_f32_e32 v169, 0xbfd49a78
	v_exp_f32_e32 v200, 0xc0549a78
	v_exp_f32_e32 v201, 0xc09f73da
	v_exp_f32_e32 v202, 0xc0d49a78
	v_exp_f32_e32 v203, 0xc104e08b
	v_exp_f32_e32 v204, 0xc11f73da
	v_exp_f32_e32 v205, 0xc13a0729
	v_lshl_add_u64 v[182:183], v[0:1], 0, s[0:1]
	v_mbcnt_lo_u32_b32 v0, -1, 0
	v_mbcnt_hi_u32_b32 v212, -1, v0
	v_lshlrev_b32_e32 v2, 15, v3
	s_mov_b32 s17, 0
	v_and_b32_e32 v4, 56, v4
	s_mov_b64 s[0:1], 0x11000180
	v_and_b32_e32 v0, 64, v212
	s_mov_b32 s15, s17
	v_lshlrev_b32_e32 v176, 3, v171
	v_lshl_add_u64 v[184:185], v[6:7], 0, s[0:1]
	v_mov_b32_e32 v210, 0x358637bd
	s_mov_b32 s64, 0xf800000
	v_mov_b32_e32 v211, 0x260
	s_mov_b32 s65, 0x3e38aa3b
	s_mov_b32 s68, 0x41000000
	s_mov_b64 s[20:21], 0x2000
	s_mov_b64 s[22:23], 0x80
	s_mov_b32 s71, 0x3e16c740
	s_mov_b64 s[36:37], 0x3000
	v_xor_b32_e32 v213, 32, v212
	v_add_u32_e32 v214, 64, v0
	v_lshlrev_b32_e32 v172, 1, v2
	v_lshlrev_b32_e32 v186, 1, v4
	v_lshlrev_b32_e32 v188, 4, v168
	v_add_u32_e32 v215, 0x4800, v198
	v_add_u32_e32 v216, 0x6800, v198
	v_mov_b32_e32 v217, 0x60000
	s_branch .LBB0_334

.LBB0_334:
	s_lshr_b32 s3, s2, 3
	s_lshl_b32 s0, s2, 6
	s_bfe_u32 s72, s2, 0x30003
	s_and_b32 s73, s0, 0xf000
	s_xor_b32 s8, s2, s46
	s_and_b32 s0, s2, 7
	s_bfe_u32 s1, s3, 0x40003
	s_cmpk_gt_u32 s8, 0x3ff
	s_mov_b64 s[42:43], -1
	s_cbranch_scc0 .LBB0_347
	s_lshl_b32 s3, s3, 16
	s_and_b32 s8, s3, 0x40000
	s_and_b32 s3, s3, 0x780000
	s_or_b32 s16, s3, s8
	s_lshl_b32 s3, s72, 20
	s_and_b32 s3, s3, 0x400000
	v_lshl_add_u64 v[190:191], v[178:179], 0, s[16:17]
	s_or_b32 s16, s73, s3
	s_lshl_b32 s75, s1, 11
	s_lshl_b32 s74, s0, 8
	v_lshl_add_u64 v[192:193], v[180:181], 0, s[16:17]
	s_or_b32 s16, s75, s74
	s_lshr_b32 s18, s72, 2
	s_mul_i32 s3, s16, 0xc00
	s_add_u32 s8, s26, s3
	s_addc_u32 s9, s27, 0
	s_lshl_b32 s3, s72, 6
	s_lshl_b32 s19, s72, 7
	s_add_u32 s8, s8, s19
	s_addc_u32 s9, s9, 0
	s_add_u32 s8, s8, 0x6000540
	s_addc_u32 s9, s9, 0
	s_lshl_b32 s19, s1, 19
	s_lshl_b32 s33, s18, 18
	s_or_b32 s19, s19, s33
	s_add_u32 s42, s92, s19
	s_addc_u32 s43, s93, 0
	s_lshl_b32 s18, s18, 22
	v_mov_b32_e32 v0, v170
	v_mov_b32_e32 v2, v171
	s_add_u32 s18, s66, s18
	s_addc_u32 s19, s67, 0
	s_lshl_b32 s33, s1, 12
	v_add_u32_e32 v3, s14, v0
	v_readlane_b32 s48, v242, 17
	v_mov_b64_e32 v[0:1], s[8:9]
	s_movk_i32 s8, 0xc00
	v_lshlrev_b32_e32 v4, 3, v2
	s_add_u32 s44, s18, s33
	v_readlane_b32 s50, v242, 19
	v_readlane_b32 s51, v242, 20
	v_mad_i64_i32 v[0:1], s[8:9], v3, s8, v[0:1]
	v_ashrrev_i32_e32 v5, 31, v4
	s_addc_u32 s45, s19, 0
	s_mov_b64 s[18:19], s[50:51]
	v_lshl_add_u64 v[0:1], v[4:5], 1, v[0:1]
	global_load_dwordx4 v[38:41], v[0:1], off
	global_load_dwordx4 v[42:45], v[0:1], off offset:32
	global_load_dwordx4 v[46:49], v[0:1], off offset:64
	global_load_dwordx4 v[50:53], v[0:1], off offset:96
	v_cmp_lt_i32_e32 vcc, v213, v214
	v_add_u32_e32 v0, s74, v3
	v_ashrrev_i32_e32 v0, 6, v0
	v_cndmask_b32_e32 v1, v212, v213, vcc
	v_lshlrev_b32_e32 v218, 2, v1
	v_cvt_f32_i32_e32 v1, v4
	v_cvt_f32_i32_e32 v6, v0
	v_and_b32_e32 v0, 63, v3
	v_cvt_f32_ubyte0_e32 v110, v0
	v_mul_f32_e32 v0, 0xbf549a78, v1
	v_exp_f32_e32 v7, v0
	v_or_b32_e32 v0, 1, v4
	v_cvt_f32_i32_e32 v1, v0
	v_lshl_add_u64 v[32:33], v[4:5], 2, s[18:19]
	v_mul_f32_e32 v0, v7, v6
	v_mul_f32_e32 v2, 0.15915494, v0
	v_mul_f32_e32 v1, 0xbf549a78, v1
	v_exp_f32_e32 v5, v1
	v_or_b32_e32 v1, 2, v4
	v_cvt_f32_i32_e32 v3, v1
	v_cos_f32_e32 v0, v2
	v_mul_f32_e32 v1, v5, v6
	v_mul_f32_e32 v8, 0.15915494, v1
	v_mul_f32_e32 v3, 0xbf549a78, v3
	v_cos_f32_e32 v1, v8
	v_exp_f32_e32 v10, v3
	v_sin_f32_e32 v3, v8
	v_or_b32_e32 v8, 3, v4
	v_cvt_f32_i32_e32 v9, v8
	v_mul_f32_e32 v8, v10, v6
	v_mul_f32_e32 v11, 0.15915494, v8
	v_cos_f32_e32 v8, v11
	v_mul_f32_e32 v9, 0xbf549a78, v9
	v_exp_f32_e32 v13, v9
	v_or_b32_e32 v9, 4, v4
	v_sin_f32_e32 v14, v11
	v_cvt_f32_i32_e32 v11, v9
	v_mul_f32_e32 v9, v13, v6
	v_mul_f32_e32 v12, 0.15915494, v9
	v_cos_f32_e32 v9, v12
	v_mul_f32_e32 v11, 0xbf549a78, v11
	v_exp_f32_e32 v20, v11
	v_or_b32_e32 v11, 5, v4
	v_cvt_f32_i32_e32 v11, v11
	v_sin_f32_e32 v15, v12
	v_mul_f32_e32 v12, v20, v6
	v_mul_f32_e32 v12, 0.15915494, v12
	v_mul_f32_e32 v11, 0xbf549a78, v11
	v_exp_f32_e32 v21, v11
	v_or_b32_e32 v11, 6, v4
	v_cvt_f32_i32_e32 v11, v11
	v_or_b32_e32 v4, 7, v4
	v_cvt_f32_i32_e32 v4, v4
	v_cos_f32_e32 v22, v12
	v_mul_f32_e32 v11, 0xbf549a78, v11
	v_exp_f32_e32 v24, v11
	v_mul_f32_e32 v4, 0xbf549a78, v4
	v_exp_f32_e32 v111, v4
	v_sin_f32_e32 v26, v12
	v_mul_f32_e32 v11, v24, v6
	v_mul_f32_e32 v4, 0.15915494, v11
	v_cos_f32_e32 v28, v4
	v_sin_f32_e32 v30, v4
	v_mul_f32_e32 v4, v111, v6
	v_mul_f32_e32 v4, 0.15915494, v4
	v_cos_f32_e32 v29, v4
	v_sin_f32_e32 v31, v4
	v_mul_f32_e32 v4, v7, v110
	v_mul_f32_e32 v4, 0.15915494, v4
	v_cos_f32_e32 v16, v4
	v_sin_f32_e32 v18, v4
	v_mul_f32_e32 v4, v5, v110
	v_mul_f32_e32 v4, 0.15915494, v4
	v_mul_f32_e32 v12, v21, v6
	v_cos_f32_e32 v17, v4
	v_sin_f32_e32 v19, v4
	s_waitcnt vmcnt(0)
	v_lshlrev_b32_e32 v106, 16, v38
	v_and_b32_e32 v107, 0xffff0000, v38
	v_lshlrev_b32_e32 v98, 16, v39
	v_and_b32_e32 v99, 0xffff0000, v39
	v_pk_mul_f32 v[38:39], v[106:107], v[106:107]
	v_pk_mul_f32 v[100:101], v[98:99], v[98:99]
	v_add_f32_e32 v38, v38, v39
	v_lshlrev_b32_e32 v92, 16, v40
	v_and_b32_e32 v93, 0xffff0000, v40
	v_add_f32_e32 v38, v100, v38
	v_lshlrev_b32_e32 v82, 16, v41
	v_and_b32_e32 v83, 0xffff0000, v41
	v_pk_mul_f32 v[40:41], v[92:93], v[92:93]
	v_add_f32_e32 v38, v101, v38
	v_add_f32_e32 v38, v40, v38
	v_pk_mul_f32 v[84:85], v[82:83], v[82:83]
	v_add_f32_e32 v38, v41, v38
	v_lshlrev_b32_e32 v108, 16, v42
	v_and_b32_e32 v109, 0xffff0000, v42
	v_add_f32_e32 v38, v84, v38
	v_lshlrev_b32_e32 v102, 16, v43
	v_and_b32_e32 v103, 0xffff0000, v43
	v_pk_mul_f32 v[42:43], v[108:109], v[108:109]
	v_add_f32_e32 v38, v85, v38
	v_add_f32_e32 v38, v42, v38
	v_pk_mul_f32 v[104:105], v[102:103], v[102:103]
	v_add_f32_e32 v38, v43, v38
	v_lshlrev_b32_e32 v94, 16, v44
	v_and_b32_e32 v95, 0xffff0000, v44
	v_add_f32_e32 v38, v104, v38
	v_pk_mul_f32 v[96:97], v[94:95], v[94:95]
	v_add_f32_e32 v38, v105, v38
	v_mul_f32_e32 v4, v10, v110
	v_lshlrev_b32_e32 v86, 16, v45
	v_and_b32_e32 v87, 0xffff0000, v45
	v_add_f32_e32 v38, v96, v38
	v_mul_f32_e32 v12, 0.15915494, v12
	v_mul_f32_e32 v4, 0.15915494, v4
	v_pk_mul_f32 v[90:91], v[86:87], v[86:87]
	v_add_f32_e32 v38, v97, v38
	v_cos_f32_e32 v23, v12
	v_sin_f32_e32 v27, v12
	v_cos_f32_e32 v10, v4
	v_sin_f32_e32 v12, v4
	v_mul_f32_e32 v4, v13, v110
	v_lshlrev_b32_e32 v76, 16, v46
	v_and_b32_e32 v77, 0xffff0000, v46
	v_add_f32_e32 v38, v90, v38
	v_mul_f32_e32 v4, 0.15915494, v4
	v_pk_mul_f32 v[78:79], v[76:77], v[76:77]
	v_add_f32_e32 v38, v91, v38
	v_cos_f32_e32 v11, v4
	v_sin_f32_e32 v13, v4
	v_mul_f32_e32 v4, v20, v110
	v_lshlrev_b32_e32 v72, 16, v47
	v_and_b32_e32 v73, 0xffff0000, v47
	v_add_f32_e32 v38, v78, v38
	v_mul_f32_e32 v5, 0.15915494, v4
	v_mul_f32_e32 v20, v24, v110
	v_pk_mul_f32 v[68:69], v[72:73], v[72:73]
	v_add_f32_e32 v38, v79, v38
	v_cos_f32_e32 v4, v5
	v_sin_f32_e32 v6, v5
	v_mul_f32_e32 v5, v21, v110
	v_mul_f32_e32 v112, 0.15915494, v20
	v_lshlrev_b32_e32 v20, 16, v49
	v_and_b32_e32 v21, 0xffff0000, v49
	v_lshlrev_b32_e32 v24, 16, v53
	v_and_b32_e32 v25, 0xffff0000, v53
	v_lshlrev_b32_e32 v34, 16, v48
	v_and_b32_e32 v35, 0xffff0000, v48
	v_lshlrev_b32_e32 v36, 16, v52
	v_and_b32_e32 v37, 0xffff0000, v52
	v_lshlrev_b32_e32 v74, 16, v51
	v_and_b32_e32 v75, 0xffff0000, v51
	v_lshlrev_b32_e32 v88, 16, v50
	v_and_b32_e32 v89, 0xffff0000, v50
	flat_load_dwordx4 v[44:47], v[32:33] offset:16
	flat_load_dwordx4 v[48:51], v[32:33]
	flat_load_dwordx4 v[52:55], v[32:33] offset:80
	flat_load_dwordx4 v[56:59], v[32:33] offset:64
	v_add_f32_e32 v38, v68, v38
	v_pk_mul_f32 v[64:65], v[34:35], v[34:35]
	v_add_f32_e32 v38, v69, v38
	v_add_f32_e32 v38, v64, v38
	v_pk_mul_f32 v[60:61], v[20:21], v[20:21]
	v_add_f32_e32 v38, v65, v38
	v_add_f32_e32 v38, v60, v38
	v_pk_mul_f32 v[80:81], v[88:89], v[88:89]
	v_add_f32_e32 v38, v61, v38
	v_add_f32_e32 v38, v80, v38
	v_pk_mul_f32 v[70:71], v[74:75], v[74:75]
	v_add_f32_e32 v38, v81, v38
	v_add_f32_e32 v38, v70, v38
	v_pk_mul_f32 v[66:67], v[36:37], v[36:37]
	v_add_f32_e32 v38, v71, v38
	v_add_f32_e32 v38, v66, v38
	v_pk_mul_f32 v[62:63], v[24:25], v[24:25]
	v_add_f32_e32 v38, v67, v38
	v_add_f32_e32 v38, v62, v38
	v_add_f32_e32 v42, v63, v38
	flat_load_dwordx4 v[38:41], v[32:33] offset:144
	flat_load_dwordx4 v[60:63], v[32:33] offset:128
	flat_load_dwordx4 v[64:67], v[32:33] offset:208
	flat_load_dwordx4 v[68:71], v[32:33] offset:192
	ds_bpermute_b32 v43, v218, v42
	v_mul_f32_e32 v78, v111, v110
	v_sin_f32_e32 v2, v2
	v_mul_f32_e32 v7, 0.15915494, v5
	v_cos_f32_e32 v5, v7
	s_waitcnt lgkmcnt(0)
	v_add_f32_e32 v32, v42, v43
	v_fmamk_f32 v32, v32, 0x3c800000, v210
	v_mul_f32_e32 v33, 0x4f800000, v32
	v_cmp_gt_f32_e32 vcc, s64, v32
	v_sin_f32_e32 v7, v7
	v_sin_f32_e32 v42, v112
	v_cndmask_b32_e32 v33, v32, v33, vcc
	v_sqrt_f32_e32 v43, v33
	v_cos_f32_e32 v32, v112
	s_mov_b32 s76, 2
	s_mov_b32 s33, 1
	v_add_u32_e32 v79, -1, v43
	v_fma_f32 v80, -v79, v43, v33
	v_cmp_ge_f32_e64 s[8:9], 0, v80
	v_add_u32_e32 v80, 1, v43
	s_mov_b32 s77, 0
	v_cndmask_b32_e64 v79, v43, v79, s[8:9]
	v_fma_f32 v43, -v80, v43, v33
	v_cmp_lt_f32_e64 s[8:9], 0, v43
	v_readlane_b32 s49, v242, 18
	v_readlane_b32 s52, v242, 21
	v_cndmask_b32_e64 v43, v79, v80, s[8:9]
	v_mul_f32_e32 v79, 0x37800000, v43
	v_cndmask_b32_e32 v43, v43, v79, vcc
	v_cmp_class_f32_e32 vcc, v33, v211
	v_readlane_b32 s53, v242, 22
	v_readlane_b32 s54, v242, 23
	v_cndmask_b32_e32 v79, v43, v33, vcc
	v_div_scale_f32 v80, s[8:9], v79, v79, s65
	v_rcp_f32_e32 v81, v80
	v_mul_f32_e32 v43, 0.15915494, v78
	v_cos_f32_e32 v33, v43
	v_sin_f32_e32 v43, v43
	v_fma_f32 v78, -v80, v81, 1.0
	v_fmac_f32_e32 v81, v78, v81
	v_div_scale_f32 v78, vcc, s65, v79, s65
	v_mul_f32_e32 v84, v78, v81
	v_fma_f32 v85, -v80, v84, v78
	v_fmac_f32_e32 v84, v85, v81
	v_fma_f32 v78, -v80, v84, v78
	v_div_fmas_f32 v78, v78, v81, v84
	v_div_fixup_f32 v78, v78, v79, s65
	v_pk_mul_f32 v[80:81], v[78:79], v[106:107] op_sel_hi:[0,1]
	v_readlane_b32 s55, v242, 24
	v_readlane_b32 s56, v242, 25
	v_readlane_b32 s57, v242, 26
	v_readlane_b32 s58, v242, 27
	v_readlane_b32 s59, v242, 28
	v_readlane_b32 s60, v242, 29
	s_waitcnt vmcnt(0)
	v_pk_mul_f32 v[48:49], v[48:49], v[80:81]
	v_pk_mul_f32 v[80:81], v[78:79], v[108:109] op_sel_hi:[0,1]
	v_pk_mul_f32 v[56:57], v[56:57], v[80:81]
	v_readlane_b32 s61, v242, 30
	v_pk_mul_f32 v[80:81], v[0:1], v[56:57]
	v_readlane_b32 s62, v242, 31
	v_pk_fma_f32 v[84:85], v[2:3], v[48:49], v[80:81]
	v_pk_mul_f32 v[2:3], v[2:3], v[56:57]
	v_cvt_pk_bf16_f32 v84, v84, v85
	v_pk_fma_f32 v[0:1], v[0:1], v[48:49], v[2:3] neg_lo:[0,0,1] neg_hi:[0,0,1]
	v_pk_mul_f32 v[48:49], v[78:79], v[102:103] op_sel_hi:[0,1]
	v_pk_mul_f32 v[2:3], v[78:79], v[98:99] op_sel_hi:[0,1]
	v_pk_mul_f32 v[48:49], v[58:59], v[48:49]
	v_pk_mul_f32 v[2:3], v[50:51], v[2:3]
	v_pk_mul_f32 v[50:51], v[8:9], v[48:49]
	v_cvt_pk_bf16_f32 v80, v0, v1
	v_pk_fma_f32 v[50:51], v[14:15], v[2:3], v[50:51]
	v_pk_mul_f32 v[14:15], v[14:15], v[48:49]
	v_pk_mul_f32 v[0:1], v[78:79], v[76:77] op_sel_hi:[0,1]
	v_pk_fma_f32 v[2:3], v[8:9], v[2:3], v[14:15] neg_lo:[0,0,1] neg_hi:[0,0,1]
	v_pk_mul_f32 v[14:15], v[78:79], v[94:95] op_sel_hi:[0,1]
	v_pk_mul_f32 v[8:9], v[78:79], v[92:93] op_sel_hi:[0,1]
	v_pk_mul_f32 v[14:15], v[52:53], v[14:15]
	v_pk_mul_f32 v[8:9], v[44:45], v[8:9]
	v_pk_mul_f32 v[44:45], v[22:23], v[14:15]
	v_pk_mul_f32 v[14:15], v[26:27], v[14:15]
	v_pk_fma_f32 v[44:45], v[26:27], v[8:9], v[44:45]
	v_pk_fma_f32 v[8:9], v[22:23], v[8:9], v[14:15] neg_lo:[0,0,1] neg_hi:[0,0,1]
	v_pk_mul_f32 v[22:23], v[78:79], v[86:87] op_sel_hi:[0,1]
	v_pk_mul_f32 v[14:15], v[78:79], v[82:83] op_sel_hi:[0,1]
	v_pk_mul_f32 v[22:23], v[54:55], v[22:23]
	v_pk_mul_f32 v[14:15], v[46:47], v[14:15]
	v_pk_mul_f32 v[26:27], v[28:29], v[22:23]
	v_pk_mul_f32 v[22:23], v[30:31], v[22:23]
	v_cvt_pk_bf16_f32 v81, v2, v3
	v_pk_mul_f32 v[2:3], v[78:79], v[88:89] op_sel_hi:[0,1]
	v_pk_fma_f32 v[26:27], v[30:31], v[14:15], v[26:27]
	v_pk_fma_f32 v[14:15], v[28:29], v[14:15], v[22:23] neg_lo:[0,0,1] neg_hi:[0,0,1]
	v_pk_mul_f32 v[2:3], v[68:69], v[2:3]
	v_cvt_pk_bf16_f32 v82, v8, v9
	v_cvt_pk_bf16_f32 v83, v14, v15
	v_pk_mul_f32 v[0:1], v[60:61], v[0:1]
	v_pk_mul_f32 v[8:9], v[16:17], v[2:3]
	v_pk_mul_f32 v[2:3], v[18:19], v[2:3]
	v_pk_mul_f32 v[14:15], v[78:79], v[74:75] op_sel_hi:[0,1]
	v_pk_fma_f32 v[8:9], v[18:19], v[0:1], v[8:9]
	v_pk_fma_f32 v[0:1], v[16:17], v[0:1], v[2:3] neg_lo:[0,0,1] neg_hi:[0,0,1]
	v_pk_mul_f32 v[2:3], v[78:79], v[72:73] op_sel_hi:[0,1]
	v_pk_mul_f32 v[14:15], v[70:71], v[14:15]
	v_pk_mul_f32 v[2:3], v[62:63], v[2:3]
	v_pk_mul_f32 v[16:17], v[10:11], v[14:15]
	v_cvt_pk_bf16_f32 v85, v50, v51
	v_pk_fma_f32 v[16:17], v[12:13], v[2:3], v[16:17]
	v_pk_mul_f32 v[12:13], v[12:13], v[14:15]
	v_cvt_pk_bf16_f32 v86, v44, v45
	v_pk_fma_f32 v[2:3], v[10:11], v[2:3], v[12:13] neg_lo:[0,0,1] neg_hi:[0,0,1]
	v_pk_mul_f32 v[12:13], v[78:79], v[36:37] op_sel_hi:[0,1]
	v_pk_mul_f32 v[10:11], v[78:79], v[34:35] op_sel_hi:[0,1]
	v_pk_mul_f32 v[12:13], v[64:65], v[12:13]
	v_pk_mul_f32 v[10:11], v[38:39], v[10:11]
	v_pk_mul_f32 v[14:15], v[4:5], v[12:13]
	v_cvt_pk_bf16_f32 v87, v26, v27
	v_pk_fma_f32 v[14:15], v[6:7], v[10:11], v[14:15]
	v_pk_mul_f32 v[6:7], v[6:7], v[12:13]
	v_cvt_pk_bf16_f32 v92, v0, v1
	v_pk_fma_f32 v[4:5], v[4:5], v[10:11], v[6:7] neg_lo:[0,0,1] neg_hi:[0,0,1]
	v_pk_mul_f32 v[10:11], v[78:79], v[24:25] op_sel_hi:[0,1]
	v_pk_mul_f32 v[6:7], v[78:79], v[20:21] op_sel_hi:[0,1]
	v_pk_mul_f32 v[10:11], v[66:67], v[10:11]
	v_pk_mul_f32 v[6:7], v[40:41], v[6:7]
	v_pk_mul_f32 v[12:13], v[32:33], v[10:11]
	v_pk_mul_f32 v[10:11], v[42:43], v[10:11]
	v_pk_fma_f32 v[12:13], v[42:43], v[6:7], v[12:13]
	v_pk_fma_f32 v[6:7], v[32:33], v[6:7], v[10:11] neg_lo:[0,0,1] neg_hi:[0,0,1]
	v_cvt_pk_bf16_f32 v93, v2, v3
	v_cvt_pk_bf16_f32 v94, v4, v5
	v_cvt_pk_bf16_f32 v95, v6, v7
	v_cvt_pk_bf16_f32 v88, v8, v9
	v_cvt_pk_bf16_f32 v89, v16, v17
	v_cvt_pk_bf16_f32 v90, v14, v15
	v_cvt_pk_bf16_f32 v91, v12, v13
	v_readlane_b32 s63, v242, 32
	v_mov_b32_e32 v189, v173
	v_lshl_add_u64 v[44:45], s[42:43], 0, v[188:189]
	s_movk_i32 s8, 0x2000
	v_lshl_add_u64 v[0:1], s[44:45], 0, v[172:173]
	v_mov_b32_e32 v187, v173
	v_add_co_u32_e32 v24, vcc, s8, v44
	v_lshl_add_u64 v[196:197], v[0:1], 0, v[186:187]
	v_mov_b32_e32 v0, v173
	v_mov_b32_e32 v1, v173
	v_mov_b32_e32 v2, v173
	v_mov_b32_e32 v3, v173
	v_mov_b32_e32 v4, v173
	v_mov_b32_e32 v5, v173
	v_mov_b32_e32 v6, v173
	v_mov_b32_e32 v7, v173
	v_mov_b32_e32 v8, v173
	v_mov_b32_e32 v9, v173
	v_mov_b32_e32 v10, v173
	v_mov_b32_e32 v11, v173
	v_mov_b32_e32 v12, v173
	v_mov_b32_e32 v13, v173
	v_mov_b32_e32 v14, v173
	v_mov_b32_e32 v15, v173
	v_addc_co_u32_e32 v25, vcc, 0, v45, vcc
	global_load_dwordx4 v[16:19], v188, s[42:43]
	global_load_dwordx4 v[20:23], v[196:197], off
	s_nop 0
	global_load_dwordx4 v[24:27], v[24:25], off
	global_load_dwordx4 v[28:31], v[196:197], off offset:128
	s_movk_i32 s8, 0x4000
	s_waitcnt vmcnt(3)
	ds_write_b128 v177, v[16:19]
	s_waitcnt vmcnt(2)
	ds_write2_b64 v215, v[20:21], v[22:23] offset1:2
	s_waitcnt vmcnt(1)
	ds_write_b128 v177, v[24:27] offset:9216
	s_waitcnt vmcnt(0)
	ds_write2_b64 v216, v[28:29], v[30:31] offset0:128 offset1:130
	s_waitcnt lgkmcnt(0)
	s_barrier
	ds_read_b128 v[32:35], v199
	ds_read_b128 v[36:39], v199 offset:32
	s_waitcnt lgkmcnt(1)
	v_mfma_f32_32x32x16_bf16 v[16:31], v[32:35], v[80:83], v[0:15]
	ds_read_b128 v[32:35], v199 offset:4608
	ds_read_b128 v[40:43], v199 offset:4640
	s_waitcnt lgkmcnt(1)
	v_mfma_f32_32x32x16_bf16 v[0:15], v[32:35], v[80:83], v[0:15]
	v_mfma_f32_32x32x16_bf16 v[16:31], v[36:39], v[84:87], v[16:31]
	ds_read_b128 v[32:35], v199 offset:64
	ds_read_b128 v[36:39], v199 offset:96
	s_waitcnt lgkmcnt(2)
	v_mfma_f32_32x32x16_bf16 v[0:15], v[40:43], v[84:87], v[0:15]
	s_waitcnt lgkmcnt(1)
	v_mfma_f32_32x32x16_bf16 v[16:31], v[32:35], v[92:95], v[16:31]
	ds_read_b128 v[32:35], v199 offset:4672
	ds_read_b128 v[40:43], v199 offset:4704
	s_waitcnt lgkmcnt(1)
	v_mfma_f32_32x32x16_bf16 v[0:15], v[32:35], v[92:95], v[0:15]
	v_add_co_u32_e32 v32, vcc, s8, v44
	s_nop 1
	v_addc_co_u32_e32 v33, vcc, 0, v45, vcc
	global_load_dwordx4 v[52:55], v[32:33], off
	global_load_dwordx4 v[48:51], v[196:197], off offset:256
	v_mfma_f32_32x32x16_bf16 v[16:31], v[36:39], v[88:91], v[16:31]
	s_waitcnt lgkmcnt(0)
	v_mfma_f32_32x32x16_bf16 v[0:15], v[40:43], v[88:91], v[0:15]
	ds_read_b128 v[96:99], v199 offset:18432
	ds_read_b128 v[68:71], v199 offset:18464
	ds_read_b128 v[100:103], v199 offset:23040
	ds_read_b128 v[72:75], v199 offset:23072
	ds_read_b128 v[64:67], v199 offset:18496
	ds_read_b128 v[60:63], v199 offset:18528
	ds_read_b128 v[76:79], v199 offset:23104
	ds_read_b128 v[56:59], v199 offset:23136
	s_nop 1
	v_max3_f32 v32, v16, v17, v18
	s_nop 0
	v_max3_f32 v33, v0, v1, v2
	v_max3_f32 v32, v32, v19, v20
	v_max3_f32 v33, v33, v3, v4
	v_max3_f32 v32, v32, v21, v22
	v_max3_f32 v33, v33, v5, v6
	v_max3_f32 v32, v32, v23, v24
	v_max3_f32 v33, v33, v7, v8
	v_max3_f32 v32, v32, v25, v26
	v_max3_f32 v33, v33, v9, v10
	v_max3_f32 v32, v32, v27, v28
	v_max3_f32 v33, v33, v11, v12
	v_max_f32_e32 v34, v15, v15
	v_max_f32_e32 v35, v31, v31
	v_max3_f32 v32, v32, v29, v30
	v_max3_f32 v33, v33, v13, v14
	v_max_f32_e32 v34, v35, v34
	v_max3_f32 v32, v32, v33, v34
	v_mov_b32_e32 v33, v32
	s_nop 1
	v_permlane32_swap_b32_e32 v32, v33
	v_max_f32_e32 v33, v33, v33
	v_max_f32_e32 v32, v32, v32
	v_max_f32_e32 v33, v32, v33
	s_cmp_eq_u32 s98, 0
	s_cbranch_scc1 .Lstg_x_1
	s_waitcnt lgkmcnt(0)
	s_barrier
.Lstg_x_1:
	v_sub_f32_e32 v0, v0, v33
	v_sub_f32_e32 v32, v7, v33
	v_sub_f32_e32 v7, v16, v33
	v_sub_f32_e32 v1, v1, v33
	v_sub_f32_e32 v34, v8, v33
	v_sub_f32_e32 v37, v11, v33
	v_sub_f32_e32 v8, v17, v33
	v_sub_f32_e32 v11, v20, v33
	v_sub_f32_e32 v20, v28, v33
	v_exp_f32_e32 v28, v7
	v_exp_f32_e32 v108, v0
	v_sub_f32_e32 v39, v13, v33
	v_sub_f32_e32 v40, v14, v33
	v_sub_f32_e32 v13, v22, v33
	v_sub_f32_e32 v14, v23, v33
	v_sub_f32_e32 v22, v29, v33
	v_sub_f32_e32 v23, v30, v33
	v_exp_f32_e32 v29, v8
	v_exp_f32_e32 v30, v1
	v_sub_f32_e32 v2, v2, v33
	v_sub_f32_e32 v35, v9, v33
	v_sub_f32_e32 v9, v18, v33
	v_sub_f32_e32 v3, v3, v33
	v_sub_f32_e32 v36, v10, v33
	v_sub_f32_e32 v41, v15, v33
	v_sub_f32_e32 v10, v19, v33
	v_sub_f32_e32 v15, v24, v33
	v_sub_f32_e32 v24, v31, v33
	v_add_f32_e32 v0, v28, v108
	v_exp_f32_e32 v31, v9
	v_exp_f32_e32 v109, v2
	v_sub_f32_e32 v4, v4, v33
	v_sub_f32_e32 v5, v5, v33
	v_sub_f32_e32 v38, v12, v33
	v_sub_f32_e32 v12, v21, v33
	v_add_f32_e32 v0, 0, v0
	v_add_f32_e32 v1, v29, v30
	v_exp_f32_e32 v104, v10
	v_exp_f32_e32 v110, v3
	v_add_f32_e32 v7, v1, v0
	v_exp_f32_e32 v1, v11
	v_exp_f32_e32 v3, v4
	v_exp_f32_e32 v0, v12
	v_exp_f32_e32 v2, v5
	v_add_f32_e32 v8, v31, v109
	v_add_f32_e32 v4, v8, v7
	v_add_f32_e32 v5, v104, v110
	v_sub_f32_e32 v6, v6, v33
	v_add_f32_e32 v7, v5, v4
	v_pk_add_f32 v[4:5], v[0:1], v[2:3]
	v_exp_f32_e32 v9, v6
	v_add_f32_e32 v5, v5, v7
	v_exp_f32_e32 v7, v13
	v_exp_f32_e32 v6, v14
	v_exp_f32_e32 v8, v32
	v_sub_f32_e32 v16, v25, v33
	v_pk_mov_b32 v[10:11], v[0:1], v[0:1] op_sel:[1,0]
	v_pk_mov_b32 v[12:13], v[2:3], v[2:3] op_sel:[1,0]
	v_add_f32_e32 v2, v4, v5
	v_pk_add_f32 v[0:1], v[6:7], v[8:9]
	v_exp_f32_e32 v3, v15
	v_add_f32_e32 v1, v1, v2
	v_exp_f32_e32 v5, v34
	v_exp_f32_e32 v2, v16
	v_exp_f32_e32 v4, v35
	v_sub_f32_e32 v17, v26, v33
	v_sub_f32_e32 v18, v27, v33
	v_add_f32_e32 v14, v0, v1
	v_pk_add_f32 v[0:1], v[2:3], v[4:5]
	v_exp_f32_e32 v15, v17
	v_add_f32_e32 v1, v1, v14
	v_exp_f32_e32 v17, v36
	v_exp_f32_e32 v14, v18
	v_exp_f32_e32 v16, v37
	v_pk_mov_b32 v[18:19], v[2:3], v[2:3] op_sel:[1,0]
	v_add_f32_e32 v2, v0, v1
	v_exp_f32_e32 v3, v20
	v_pk_add_f32 v[0:1], v[14:15], v[16:17]
	v_exp_f32_e32 v21, v38
	v_add_f32_e32 v1, v1, v2
	v_exp_f32_e32 v2, v22
	v_exp_f32_e32 v20, v39
	v_add_f32_e32 v22, v0, v1
	v_exp_f32_e32 v23, v23
	v_exp_f32_e32 v25, v40
	v_pk_add_f32 v[0:1], v[2:3], v[20:21]
	v_pk_mov_b32 v[26:27], v[2:3], v[2:3] op_sel:[1,0]
	v_add_f32_e32 v1, v1, v22
	v_exp_f32_e32 v22, v24
	v_exp_f32_e32 v24, v41
	v_add_f32_e32 v2, v0, v1
	v_pk_mov_b32 v[6:7], v[6:7], v[6:7] op_sel:[1,0]
	v_pk_mov_b32 v[8:9], v[8:9], v[8:9] op_sel:[1,0]
	v_pk_add_f32 v[0:1], v[22:23], v[24:25]
	v_pk_mov_b32 v[4:5], v[4:5], v[4:5] op_sel:[1,0]
	v_add_f32_e32 v1, v1, v2
	v_add_f32_e32 v32, v0, v1
	v_pk_add_f32 v[194:195], v[32:33], 0 op_sel_hi:[1,0]
	v_pk_mov_b32 v[14:15], v[14:15], v[14:15] op_sel:[1,0]
	v_xor_b32_e32 v32, 0x80000000, v195
	v_pk_mov_b32 v[16:17], v[16:17], v[16:17] op_sel:[1,0]
	v_pk_mov_b32 v[20:21], v[20:21], v[20:21] op_sel:[1,0]
	v_pk_mov_b32 v[22:23], v[22:23], v[22:23] op_sel:[1,0]
	v_pk_mov_b32 v[24:25], v[24:25], v[24:25] op_sel:[1,0]
	v_mov_b32_e32 v33, v32
	v_mov_b32_e32 v34, v32
	v_mov_b32_e32 v35, v32
	v_mov_b32_e32 v36, v32
	v_mov_b32_e32 v37, v32
	v_mov_b32_e32 v38, v32
	v_mov_b32_e32 v39, v32
	v_mov_b32_e32 v40, v32
	v_mov_b32_e32 v41, v32
	v_mov_b32_e32 v42, v32
	v_mov_b32_e32 v43, v32
	v_mov_b32_e32 v44, v32
	v_mov_b32_e32 v45, v32
	v_mov_b32_e32 v46, v32
	v_mov_b32_e32 v47, v32
	v_cvt_pk_bf16_f32 v0, v28, v29
	v_cvt_pk_bf16_f32 v1, v31, v104
	v_cvt_pk_bf16_f32 v2, v10, v11
	v_cvt_pk_bf16_f32 v3, v6, v7
	v_cvt_pk_bf16_f32 v104, v18, v19
	v_cvt_pk_bf16_f32 v105, v14, v15
	v_cvt_pk_bf16_f32 v106, v26, v27
	v_cvt_pk_bf16_f32 v107, v22, v23
	v_cvt_pk_bf16_f32 v108, v108, v30
	v_cvt_pk_bf16_f32 v109, v109, v110
	v_cvt_pk_bf16_f32 v110, v12, v13
	v_cvt_pk_bf16_f32 v111, v8, v9
	v_cvt_pk_bf16_f32 v112, v4, v5
	v_cvt_pk_bf16_f32 v113, v16, v17
	v_cvt_pk_bf16_f32 v114, v20, v21
	v_cvt_pk_bf16_f32 v115, v24, v25
	s_cmp_lg_u32 s98, 0
	s_cbranch_scc1 .Lstg_y_2
	s_waitcnt lgkmcnt(0)
	s_barrier
.Lstg_y_2:
	ds_read_b128 v[160:163], v199 offset:9216
	ds_read_b128 v[156:159], v199 offset:9248
	ds_read_b128 v[164:167], v199 offset:13824
	ds_read_b128 v[152:155], v199 offset:13856
	ds_read_b128 v[144:147], v199 offset:9280
	ds_read_b128 v[140:143], v199 offset:9312
	ds_read_b128 v[148:151], v199 offset:13888
	ds_read_b128 v[136:139], v199 offset:13920
	s_waitcnt lgkmcnt(14)
	v_mfma_f32_32x32x16_bf16 v[16:31], v[96:99], v[0:3], 0
	s_waitcnt vmcnt(1)
	ds_write_b128 v177, v[52:55]
	s_waitcnt vmcnt(0)
	ds_write2_b64 v215, v[48:49], v[50:51] offset1:2
	s_waitcnt lgkmcnt(14)
	v_mfma_f32_32x32x16_bf16 v[0:15], v[100:103], v[0:3], 0
	v_mfma_f32_32x32x16_bf16 v[16:31], v[68:71], v[104:107], v[16:31]
	v_mfma_f32_32x32x16_bf16 v[0:15], v[72:75], v[104:107], v[0:15]
	s_waitcnt lgkmcnt(13)
	v_mfma_f32_32x32x16_bf16 v[16:31], v[64:67], v[108:111], v[16:31]
	s_waitcnt lgkmcnt(11)
	v_mfma_f32_32x32x16_bf16 v[0:15], v[76:79], v[108:111], v[0:15]
	v_mfma_f32_32x32x16_bf16 v[16:31], v[60:63], v[112:115], v[16:31]
	s_waitcnt lgkmcnt(10)
	v_mfma_f32_32x32x16_bf16 v[0:15], v[56:59], v[112:115], v[0:15]
.LBB0_336:
	global_load_dwordx4 v[104:107], v[190:191], off
	global_load_dwordx4 v[96:99], v[192:193], off
	s_waitcnt lgkmcnt(9)
	v_mfma_f32_32x32x16_bf16 v[64:79], v[160:163], v[80:83], v[32:47]
	s_mov_b32 s8, s33
	s_waitcnt lgkmcnt(7)
	v_mfma_f32_32x32x16_bf16 v[48:63], v[164:167], v[80:83], v[32:47]
	v_mfma_f32_32x32x16_bf16 v[64:79], v[156:159], v[84:87], v[64:79]
	s_waitcnt lgkmcnt(6)
	v_mfma_f32_32x32x16_bf16 v[48:63], v[152:155], v[84:87], v[48:63]
	s_waitcnt lgkmcnt(5)
	v_mfma_f32_32x32x16_bf16 v[64:79], v[144:147], v[92:95], v[64:79]
	s_waitcnt lgkmcnt(3)
	v_mfma_f32_32x32x16_bf16 v[48:63], v[148:151], v[92:95], v[48:63]
	v_mfma_f32_32x32x16_bf16 v[64:79], v[140:143], v[88:91], v[64:79]
	s_waitcnt lgkmcnt(2)
	v_mfma_f32_32x32x16_bf16 v[48:63], v[136:139], v[88:91], v[48:63]
	s_and_b32 s33, 1, s76
	s_cselect_b32 s9, 0, 0x2400
	v_add_u32_e32 v100, s9, v199
	ds_read_b128 v[128:131], v100 offset:18432
	ds_read_b128 v[116:119], v100 offset:18464
	ds_read_b128 v[132:135], v100 offset:23040
	ds_read_b128 v[120:123], v100 offset:23072
	ds_read_b128 v[112:115], v100 offset:18496
	ds_read_b128 v[108:111], v100 offset:18528
	ds_read_b128 v[124:127], v100 offset:23104
	ds_read_b128 v[100:103], v100 offset:23136
	v_max3_f32 v136, v64, v65, v66
	v_max3_f32 v137, v48, v49, v50
	v_max3_f32 v136, v136, v67, v68
	v_max3_f32 v137, v137, v51, v52
	v_max3_f32 v136, v136, v69, v70
	v_max3_f32 v137, v137, v53, v54
	v_max3_f32 v136, v136, v71, v72
	v_max3_f32 v137, v137, v55, v56
	v_max3_f32 v136, v136, v73, v74
	v_max3_f32 v137, v137, v57, v58
	v_max3_f32 v136, v136, v75, v76
	v_max3_f32 v137, v137, v59, v60
	v_max_f32_e32 v138, v63, v63
	v_max_f32_e32 v139, v79, v79
	v_max3_f32 v136, v136, v77, v78
	v_max3_f32 v137, v137, v61, v62
	v_max_f32_e32 v138, v139, v138
	v_max3_f32 v136, v136, v137, v138
	v_mov_b32_e32 v137, v136
	s_nop 1
	v_permlane32_swap_b32_e32 v136, v137
	v_max_f32_e32 v137, v137, v137
	v_max_f32_e32 v136, v136, v136
	v_max_f32_e32 v136, v136, v137
	s_cmp_eq_u32 s98, 0
	s_cbranch_scc1 .Lstg_x_3
	s_waitcnt lgkmcnt(0)
	s_barrier
.Lstg_x_3:
	v_cmp_lt_f32_e32 vcc, s68, v136
	s_cbranch_vccz .LBB0_338
	v_max_f32_e32 v32, v136, v136
	v_max_f32_e32 v32, 0, v32
	v_exp_f32_e64 v34, -v32
	v_pk_add_f32 v[64:65], v[64:65], v[32:33] op_sel_hi:[1,0] neg_lo:[0,1] neg_hi:[0,1]
	v_pk_add_f32 v[48:49], v[48:49], v[32:33] op_sel_hi:[1,0] neg_lo:[0,1] neg_hi:[0,1]
	v_pk_add_f32 v[66:67], v[66:67], v[32:33] op_sel_hi:[1,0] neg_lo:[0,1] neg_hi:[0,1]
	v_pk_mul_f32 v[14:15], v[14:15], v[34:35] op_sel_hi:[1,0]
	v_pk_mul_f32 v[12:13], v[12:13], v[34:35] op_sel_hi:[1,0]
	v_pk_mul_f32 v[10:11], v[10:11], v[34:35] op_sel_hi:[1,0]
	v_pk_mul_f32 v[8:9], v[8:9], v[34:35] op_sel_hi:[1,0]
	v_pk_mul_f32 v[6:7], v[6:7], v[34:35] op_sel_hi:[1,0]
	v_pk_mul_f32 v[4:5], v[4:5], v[34:35] op_sel_hi:[1,0]
	v_pk_mul_f32 v[2:3], v[2:3], v[34:35] op_sel_hi:[1,0]
	v_pk_mul_f32 v[0:1], v[0:1], v[34:35] op_sel_hi:[1,0]
	v_pk_mul_f32 v[30:31], v[30:31], v[34:35] op_sel_hi:[1,0]
	v_pk_mul_f32 v[28:29], v[28:29], v[34:35] op_sel_hi:[1,0]
	v_pk_mul_f32 v[26:27], v[26:27], v[34:35] op_sel_hi:[1,0]
	v_pk_mul_f32 v[24:25], v[24:25], v[34:35] op_sel_hi:[1,0]
	v_pk_mul_f32 v[22:23], v[22:23], v[34:35] op_sel_hi:[1,0]
	v_pk_mul_f32 v[20:21], v[20:21], v[34:35] op_sel_hi:[1,0]
	v_pk_mul_f32 v[18:19], v[18:19], v[34:35] op_sel_hi:[1,0]
	v_pk_mul_f32 v[16:17], v[16:17], v[34:35] op_sel_hi:[1,0]
	v_mov_b32_e32 v35, v32
	v_pk_add_f32 v[50:51], v[50:51], v[32:33] op_sel_hi:[1,0] neg_lo:[0,1] neg_hi:[0,1]
	v_pk_add_f32 v[68:69], v[68:69], v[32:33] op_sel_hi:[1,0] neg_lo:[0,1] neg_hi:[0,1]
	v_pk_add_f32 v[52:53], v[52:53], v[32:33] op_sel_hi:[1,0] neg_lo:[0,1] neg_hi:[0,1]
	v_pk_add_f32 v[70:71], v[70:71], v[32:33] op_sel_hi:[1,0] neg_lo:[0,1] neg_hi:[0,1]
	v_pk_add_f32 v[54:55], v[54:55], v[32:33] op_sel_hi:[1,0] neg_lo:[0,1] neg_hi:[0,1]
	v_pk_add_f32 v[72:73], v[72:73], v[32:33] op_sel_hi:[1,0] neg_lo:[0,1] neg_hi:[0,1]
	v_pk_add_f32 v[56:57], v[56:57], v[32:33] op_sel_hi:[1,0] neg_lo:[0,1] neg_hi:[0,1]
	v_pk_add_f32 v[74:75], v[74:75], v[32:33] op_sel_hi:[1,0] neg_lo:[0,1] neg_hi:[0,1]
	v_pk_add_f32 v[58:59], v[58:59], v[32:33] op_sel_hi:[1,0] neg_lo:[0,1] neg_hi:[0,1]
	v_pk_add_f32 v[76:77], v[76:77], v[32:33] op_sel_hi:[1,0] neg_lo:[0,1] neg_hi:[0,1]
	v_pk_add_f32 v[60:61], v[60:61], v[32:33] op_sel_hi:[1,0] neg_lo:[0,1] neg_hi:[0,1]
	v_pk_add_f32 v[78:79], v[78:79], v[32:33] op_sel_hi:[1,0] neg_lo:[0,1] neg_hi:[0,1]
	v_pk_add_f32 v[62:63], v[62:63], v[32:33] op_sel_hi:[1,0] neg_lo:[0,1] neg_hi:[0,1]
	v_pk_add_f32 v[32:33], v[194:195], v[34:35]
	v_pk_mul_f32 v[194:195], v[194:195], v[34:35]
	v_xor_b32_e32 v32, 0x80000000, v33
	v_mov_b32_e32 v195, v33
	v_mov_b32_e32 v33, v32
	v_mov_b32_e32 v34, v32
	v_mov_b32_e32 v35, v32
	v_mov_b32_e32 v36, v32
	v_mov_b32_e32 v37, v32
	v_mov_b32_e32 v38, v32
	v_mov_b32_e32 v39, v32
	v_mov_b32_e32 v40, v32
	v_mov_b32_e32 v41, v32
	v_mov_b32_e32 v42, v32
	v_mov_b32_e32 v43, v32
	v_mov_b32_e32 v44, v32
	v_mov_b32_e32 v45, v32
	v_mov_b32_e32 v46, v32
	v_mov_b32_e32 v47, v32
.LBB0_338:
	v_exp_f32_e32 v136, v64
	v_exp_f32_e32 v137, v48
	v_exp_f32_e32 v138, v65
	v_exp_f32_e32 v139, v49
	v_exp_f32_e32 v140, v66
	v_exp_f32_e32 v141, v50
	v_exp_f32_e32 v142, v67
	v_exp_f32_e32 v143, v51
	v_add_f32_e32 v48, v137, v136
	v_add_f32_e32 v48, 0, v48
	v_add_f32_e32 v49, v139, v138
	v_add_f32_e32 v48, v49, v48
	v_add_f32_e32 v49, v141, v140
	v_exp_f32_e32 v144, v68
	v_exp_f32_e32 v145, v52
	v_add_f32_e32 v48, v49, v48
	v_add_f32_e32 v49, v143, v142
	v_exp_f32_e32 v146, v69
	v_exp_f32_e32 v147, v53
	v_add_f32_e32 v52, v49, v48
	v_exp_f32_e32 v49, v70
	v_exp_f32_e32 v51, v54
	v_exp_f32_e32 v48, v71
	v_exp_f32_e32 v50, v55
	v_add_f32_e32 v64, v145, v144
	v_add_f32_e32 v52, v64, v52
	v_add_f32_e32 v53, v147, v146
	v_add_f32_e32 v54, v53, v52
	v_pk_add_f32 v[52:53], v[50:51], v[48:49]
	v_exp_f32_e32 v55, v72
	v_add_f32_e32 v53, v53, v54
	v_exp_f32_e32 v65, v56
	v_exp_f32_e32 v54, v73
	v_exp_f32_e32 v64, v57
	v_pk_mov_b32 v[56:57], v[48:49], v[48:49] op_sel:[1,0]
	v_pk_mov_b32 v[66:67], v[50:51], v[50:51] op_sel:[1,0]
	v_add_f32_e32 v50, v52, v53
	v_pk_add_f32 v[48:49], v[64:65], v[54:55]
	v_exp_f32_e32 v51, v74
	v_add_f32_e32 v49, v49, v50
	v_exp_f32_e32 v53, v58
	v_exp_f32_e32 v50, v75
	v_exp_f32_e32 v52, v59
	v_add_f32_e32 v58, v48, v49
	v_exp_f32_e32 v59, v76
	v_exp_f32_e32 v69, v60
	v_pk_add_f32 v[48:49], v[52:53], v[50:51]
	v_exp_f32_e32 v68, v61
	v_add_f32_e32 v49, v49, v58
	v_exp_f32_e32 v58, v77
	v_pk_mov_b32 v[60:61], v[50:51], v[50:51] op_sel:[1,0]
	v_add_f32_e32 v50, v48, v49
	v_pk_mov_b32 v[70:71], v[52:53], v[52:53] op_sel:[1,0]
	v_pk_add_f32 v[48:49], v[68:69], v[58:59]
	v_exp_f32_e32 v51, v78
	v_add_f32_e32 v49, v49, v50
	v_exp_f32_e32 v53, v62
	v_exp_f32_e32 v50, v79
	v_exp_f32_e32 v52, v63
	v_pk_mov_b32 v[62:63], v[68:69], v[68:69] op_sel:[1,0]
	v_add_f32_e32 v68, v48, v49
	v_pk_mov_b32 v[54:55], v[54:55], v[54:55] op_sel:[1,0]
	v_pk_add_f32 v[48:49], v[52:53], v[50:51]
	v_pk_mov_b32 v[64:65], v[64:65], v[64:65] op_sel:[1,0]
	v_add_f32_e32 v49, v49, v68
	v_add_f32_e32 v48, v48, v49
	v_pk_mov_b32 v[58:59], v[58:59], v[58:59] op_sel:[1,0]
	v_pk_mov_b32 v[68:69], v[50:51], v[50:51] op_sel:[1,0]
	v_pk_mov_b32 v[72:73], v[52:53], v[52:53] op_sel:[1,0]
	v_add_f32_e32 v194, v194, v48
	v_cvt_pk_bf16_f32 v48, v136, v138
	v_cvt_pk_bf16_f32 v49, v140, v142
	v_cvt_pk_bf16_f32 v50, v144, v146
	v_cvt_pk_bf16_f32 v51, v56, v57
	v_cvt_pk_bf16_f32 v52, v54, v55
	v_cvt_pk_bf16_f32 v53, v60, v61
	v_cvt_pk_bf16_f32 v54, v58, v59
	v_cvt_pk_bf16_f32 v55, v68, v69
	v_cvt_pk_bf16_f32 v56, v137, v139
	v_cvt_pk_bf16_f32 v57, v141, v143
	v_cvt_pk_bf16_f32 v58, v145, v147
	v_cvt_pk_bf16_f32 v59, v66, v67
	v_cvt_pk_bf16_f32 v60, v64, v65
	v_cvt_pk_bf16_f32 v61, v70, v71
	v_cvt_pk_bf16_f32 v62, v62, v63
	v_cvt_pk_bf16_f32 v63, v72, v73
	s_cmp_lg_u32 s98, 0
	s_cbranch_scc1 .Lstg_y_4
	s_waitcnt lgkmcnt(0)
	s_barrier
.Lstg_y_4:
	s_mul_i32 s9, s77, 0x2400
	v_add_u32_e32 v64, s9, v199
	ds_read_b128 v[160:163], v64
	ds_read_b128 v[156:159], v64 offset:32
	ds_read_b128 v[164:167], v64 offset:4608
	ds_read_b128 v[152:155], v64 offset:4640
	ds_read_b128 v[144:147], v64 offset:64
	ds_read_b128 v[140:143], v64 offset:96
	ds_read_b128 v[148:151], v64 offset:4672
	ds_read_b128 v[136:139], v64 offset:4704
	s_waitcnt lgkmcnt(14)
	v_mfma_f32_32x32x16_bf16 v[16:31], v[128:131], v[48:51], v[16:31]
	s_mul_i32 s9, s8, 0x2400
	s_cmp_eq_u32 s33, 1
	s_cselect_b32 s18, 0, 0x2400
	s_add_i32 s76, s76, 1
	v_lshl_add_u64 v[190:191], v[190:191], 0, s[20:21]
	v_lshl_add_u64 v[192:193], v[192:193], 0, s[22:23]
	s_cmp_eq_u32 s76, 31
	s_waitcnt lgkmcnt(13)
	v_mfma_f32_32x32x16_bf16 v[0:15], v[132:135], v[48:51], v[0:15]
	v_add_u32_e32 v48, s9, v177
	s_waitcnt vmcnt(1)
	ds_write_b128 v48, v[104:107]
	v_add_u32_e32 v48, s18, v198
	v_add_u32_e32 v48, 0x4800, v48
	s_waitcnt vmcnt(0)
	ds_write2_b64 v48, v[96:97], v[98:99] offset1:2
	v_mfma_f32_32x32x16_bf16 v[16:31], v[116:119], v[52:55], v[16:31]
	s_waitcnt lgkmcnt(14)
	v_mfma_f32_32x32x16_bf16 v[0:15], v[120:123], v[52:55], v[0:15]
	s_waitcnt lgkmcnt(13)
	v_mfma_f32_32x32x16_bf16 v[16:31], v[112:115], v[56:59], v[16:31]
	s_waitcnt lgkmcnt(11)
	v_mfma_f32_32x32x16_bf16 v[0:15], v[124:127], v[56:59], v[0:15]
	v_mfma_f32_32x32x16_bf16 v[16:31], v[108:111], v[60:63], v[16:31]
	s_waitcnt lgkmcnt(10)
	v_mfma_f32_32x32x16_bf16 v[0:15], v[100:103], v[60:63], v[0:15]
	s_cbranch_scc1 .LBB0_340
	s_mov_b32 s33, s77
	s_mov_b32 s77, s8
	s_branch .LBB0_336
.LBB0_340:
	s_waitcnt lgkmcnt(9)
	v_mfma_f32_32x32x16_bf16 v[64:79], v[160:163], v[80:83], v[32:47]
	s_waitcnt lgkmcnt(7)
	v_mfma_f32_32x32x16_bf16 v[48:63], v[164:167], v[80:83], v[32:47]
	v_mfma_f32_32x32x16_bf16 v[64:79], v[156:159], v[84:87], v[64:79]
	s_waitcnt lgkmcnt(6)
	v_mfma_f32_32x32x16_bf16 v[48:63], v[152:155], v[84:87], v[48:63]
	s_waitcnt lgkmcnt(5)
	v_mfma_f32_32x32x16_bf16 v[64:79], v[144:147], v[92:95], v[64:79]
	s_waitcnt lgkmcnt(3)
	v_mfma_f32_32x32x16_bf16 v[48:63], v[148:151], v[92:95], v[48:63]
	v_mfma_f32_32x32x16_bf16 v[64:79], v[140:143], v[88:91], v[64:79]
	s_waitcnt lgkmcnt(2)
	v_mfma_f32_32x32x16_bf16 v[48:63], v[136:139], v[88:91], v[48:63]
	ds_read_b128 v[124:127], v199 offset:18432
	ds_read_b128 v[112:115], v199 offset:18464
	ds_read_b128 v[128:131], v199 offset:23040
	ds_read_b128 v[116:119], v199 offset:23072
	ds_read_b128 v[108:111], v199 offset:18496
	ds_read_b128 v[100:103], v199 offset:18528
	ds_read_b128 v[120:123], v199 offset:23104
	ds_read_b128 v[104:107], v199 offset:23136
	s_nop 1
	v_max3_f32 v132, v64, v65, v66
	s_nop 0
	v_max3_f32 v133, v48, v49, v50
	v_max3_f32 v132, v132, v67, v68
	v_max3_f32 v133, v133, v51, v52
	v_max3_f32 v132, v132, v69, v70
	v_max3_f32 v133, v133, v53, v54
	v_max3_f32 v132, v132, v71, v72
	v_max3_f32 v133, v133, v55, v56
	v_max3_f32 v132, v132, v73, v74
	v_max3_f32 v133, v133, v57, v58
	v_max3_f32 v132, v132, v75, v76
	v_max3_f32 v133, v133, v59, v60
	v_max_f32_e32 v134, v63, v63
	v_max_f32_e32 v135, v79, v79
	v_max3_f32 v132, v132, v77, v78
	v_max3_f32 v133, v133, v61, v62
	v_max_f32_e32 v134, v135, v134
	v_max3_f32 v132, v132, v133, v134
	v_mov_b32_e32 v133, v132
	s_nop 1
	v_permlane32_swap_b32_e32 v132, v133
	v_max_f32_e32 v133, v133, v133
	v_max_f32_e32 v132, v132, v132
	v_max_f32_e32 v132, v132, v133
	s_cmp_eq_u32 s98, 0
	s_cbranch_scc1 .Lstg_x_5
	s_waitcnt lgkmcnt(0)
	s_barrier
.Lstg_x_5:
	v_cmp_lt_f32_e32 vcc, s68, v132
	s_cbranch_vccz .LBB0_342
	v_max_f32_e32 v32, v132, v132
	v_max_f32_e32 v34, 0, v32
	v_exp_f32_e64 v36, -v34
	v_add_f32_e32 v195, v195, v34
	v_xor_b32_e32 v32, 0x80000000, v195
	v_pk_add_f32 v[64:65], v[64:65], v[34:35] op_sel_hi:[1,0] neg_lo:[0,1] neg_hi:[0,1]
	v_pk_mul_f32 v[14:15], v[14:15], v[36:37] op_sel_hi:[1,0]
	v_pk_mul_f32 v[12:13], v[12:13], v[36:37] op_sel_hi:[1,0]
	v_pk_mul_f32 v[10:11], v[10:11], v[36:37] op_sel_hi:[1,0]
	v_pk_mul_f32 v[8:9], v[8:9], v[36:37] op_sel_hi:[1,0]
	v_pk_mul_f32 v[6:7], v[6:7], v[36:37] op_sel_hi:[1,0]
	v_pk_mul_f32 v[4:5], v[4:5], v[36:37] op_sel_hi:[1,0]
	v_pk_mul_f32 v[2:3], v[2:3], v[36:37] op_sel_hi:[1,0]
	v_pk_mul_f32 v[0:1], v[0:1], v[36:37] op_sel_hi:[1,0]
	v_pk_add_f32 v[48:49], v[48:49], v[34:35] op_sel_hi:[1,0] neg_lo:[0,1] neg_hi:[0,1]
	v_pk_add_f32 v[66:67], v[66:67], v[34:35] op_sel_hi:[1,0] neg_lo:[0,1] neg_hi:[0,1]
	v_pk_add_f32 v[50:51], v[50:51], v[34:35] op_sel_hi:[1,0] neg_lo:[0,1] neg_hi:[0,1]
	v_pk_add_f32 v[68:69], v[68:69], v[34:35] op_sel_hi:[1,0] neg_lo:[0,1] neg_hi:[0,1]
	v_pk_add_f32 v[52:53], v[52:53], v[34:35] op_sel_hi:[1,0] neg_lo:[0,1] neg_hi:[0,1]
	v_pk_add_f32 v[70:71], v[70:71], v[34:35] op_sel_hi:[1,0] neg_lo:[0,1] neg_hi:[0,1]
	v_pk_add_f32 v[54:55], v[54:55], v[34:35] op_sel_hi:[1,0] neg_lo:[0,1] neg_hi:[0,1]
	v_pk_add_f32 v[72:73], v[72:73], v[34:35] op_sel_hi:[1,0] neg_lo:[0,1] neg_hi:[0,1]
	v_pk_add_f32 v[56:57], v[56:57], v[34:35] op_sel_hi:[1,0] neg_lo:[0,1] neg_hi:[0,1]
	v_pk_add_f32 v[74:75], v[74:75], v[34:35] op_sel_hi:[1,0] neg_lo:[0,1] neg_hi:[0,1]
	v_pk_add_f32 v[58:59], v[58:59], v[34:35] op_sel_hi:[1,0] neg_lo:[0,1] neg_hi:[0,1]
	v_pk_add_f32 v[76:77], v[76:77], v[34:35] op_sel_hi:[1,0] neg_lo:[0,1] neg_hi:[0,1]
	v_pk_add_f32 v[60:61], v[60:61], v[34:35] op_sel_hi:[1,0] neg_lo:[0,1] neg_hi:[0,1]
	v_pk_add_f32 v[78:79], v[78:79], v[34:35] op_sel_hi:[1,0] neg_lo:[0,1] neg_hi:[0,1]
	v_pk_add_f32 v[62:63], v[62:63], v[34:35] op_sel_hi:[1,0] neg_lo:[0,1] neg_hi:[0,1]
	v_pk_mul_f32 v[30:31], v[30:31], v[36:37] op_sel_hi:[1,0]
	v_pk_mul_f32 v[28:29], v[28:29], v[36:37] op_sel_hi:[1,0]
	v_pk_mul_f32 v[26:27], v[26:27], v[36:37] op_sel_hi:[1,0]
	v_pk_mul_f32 v[24:25], v[24:25], v[36:37] op_sel_hi:[1,0]
	v_pk_mul_f32 v[22:23], v[22:23], v[36:37] op_sel_hi:[1,0]
	v_pk_mul_f32 v[20:21], v[20:21], v[36:37] op_sel_hi:[1,0]
	v_pk_mul_f32 v[18:19], v[18:19], v[36:37] op_sel_hi:[1,0]
	v_pk_mul_f32 v[16:17], v[16:17], v[36:37] op_sel_hi:[1,0]
	v_mul_f32_e32 v194, v194, v36
	v_mov_b32_e32 v33, v32
	v_mov_b32_e32 v34, v32
	v_mov_b32_e32 v35, v32
	v_mov_b32_e32 v36, v32
	v_mov_b32_e32 v37, v32
	v_mov_b32_e32 v38, v32
	v_mov_b32_e32 v39, v32
	v_mov_b32_e32 v40, v32
	v_mov_b32_e32 v41, v32
	v_mov_b32_e32 v42, v32
	v_mov_b32_e32 v43, v32
	v_mov_b32_e32 v44, v32
	v_mov_b32_e32 v45, v32
	v_mov_b32_e32 v46, v32
	v_mov_b32_e32 v47, v32
.LBB0_342:
	v_exp_f32_e32 v133, v64
	v_exp_f32_e32 v134, v48
	v_exp_f32_e32 v135, v65
	v_exp_f32_e32 v136, v49
	v_exp_f32_e32 v137, v66
	v_add_f32_e32 v48, v134, v133
	v_exp_f32_e32 v138, v50
	v_add_f32_e32 v48, 0, v48
	v_add_f32_e32 v49, v136, v135
	v_exp_f32_e32 v139, v67
	v_exp_f32_e32 v140, v51
	v_add_f32_e32 v64, v49, v48
	v_exp_f32_e32 v49, v68
	v_exp_f32_e32 v51, v52
	v_exp_f32_e32 v48, v69
	v_exp_f32_e32 v50, v53
	v_add_f32_e32 v65, v138, v137
	v_add_f32_e32 v52, v65, v64
	v_add_f32_e32 v53, v140, v139
	v_add_f32_e32 v64, v53, v52
	v_pk_add_f32 v[52:53], v[50:51], v[48:49]
	v_exp_f32_e32 v65, v70
	v_add_f32_e32 v53, v53, v64
	v_exp_f32_e32 v67, v54
	v_exp_f32_e32 v64, v71
	v_exp_f32_e32 v66, v55
	v_pk_mov_b32 v[54:55], v[48:49], v[48:49] op_sel:[1,0]
	v_pk_mov_b32 v[68:69], v[50:51], v[50:51] op_sel:[1,0]
	v_add_f32_e32 v50, v52, v53
	v_pk_add_f32 v[48:49], v[66:67], v[64:65]
	v_exp_f32_e32 v51, v72
	v_add_f32_e32 v49, v49, v50
	v_exp_f32_e32 v53, v56
	v_exp_f32_e32 v50, v73
	v_exp_f32_e32 v52, v57
	v_pk_mov_b32 v[56:57], v[64:65], v[64:65] op_sel:[1,0]
	v_pk_mov_b32 v[64:65], v[66:67], v[66:67] op_sel:[1,0]
	v_add_f32_e32 v66, v48, v49
	v_pk_add_f32 v[48:49], v[52:53], v[50:51]
	v_exp_f32_e32 v67, v74
	v_add_f32_e32 v49, v49, v66
	v_exp_f32_e32 v71, v58
	v_exp_f32_e32 v66, v75
	v_exp_f32_e32 v70, v59
	v_pk_mov_b32 v[58:59], v[50:51], v[50:51] op_sel:[1,0]
	v_add_f32_e32 v50, v48, v49
	v_pk_mov_b32 v[72:73], v[52:53], v[52:53] op_sel:[1,0]
	v_pk_add_f32 v[48:49], v[70:71], v[66:67]
	v_exp_f32_e32 v51, v76
	v_add_f32_e32 v49, v49, v50
	v_exp_f32_e32 v53, v60
	v_exp_f32_e32 v50, v77
	v_exp_f32_e32 v52, v61
	v_pk_mov_b32 v[60:61], v[66:67], v[66:67] op_sel:[1,0]
	v_pk_mov_b32 v[66:67], v[70:71], v[70:71] op_sel:[1,0]
	v_add_f32_e32 v70, v48, v49
	v_pk_add_f32 v[48:49], v[52:53], v[50:51]
	v_exp_f32_e32 v71, v78
	v_add_f32_e32 v49, v49, v70
	v_exp_f32_e32 v75, v62
	v_exp_f32_e32 v70, v79
	v_exp_f32_e32 v74, v63
	v_pk_mov_b32 v[62:63], v[50:51], v[50:51] op_sel:[1,0]
	v_add_f32_e32 v50, v48, v49
	v_pk_mov_b32 v[76:77], v[52:53], v[52:53] op_sel:[1,0]
	v_pk_add_f32 v[48:49], v[74:75], v[70:71]
	v_pk_mov_b32 v[70:71], v[70:71], v[70:71] op_sel:[1,0]
	v_add_f32_e32 v49, v49, v50
	v_pk_mov_b32 v[74:75], v[74:75], v[74:75] op_sel:[1,0]
	v_add_f32_e32 v48, v48, v49
	v_add_f32_e32 v132, v194, v48
	v_cvt_pk_bf16_f32 v48, v133, v135
	v_cvt_pk_bf16_f32 v49, v137, v139
	v_cvt_pk_bf16_f32 v50, v54, v55
	v_cvt_pk_bf16_f32 v51, v56, v57
	v_cvt_pk_bf16_f32 v52, v58, v59
	v_cvt_pk_bf16_f32 v53, v60, v61
	v_cvt_pk_bf16_f32 v54, v62, v63
	v_cvt_pk_bf16_f32 v55, v70, v71
	v_cvt_pk_bf16_f32 v56, v134, v136
	v_cvt_pk_bf16_f32 v57, v138, v140
	v_cvt_pk_bf16_f32 v58, v68, v69
	v_cvt_pk_bf16_f32 v59, v64, v65
	v_cvt_pk_bf16_f32 v60, v72, v73
	v_cvt_pk_bf16_f32 v61, v66, v67
	v_cvt_pk_bf16_f32 v62, v76, v77
	v_cvt_pk_bf16_f32 v63, v74, v75
	s_cmp_lg_u32 s98, 0
	s_cbranch_scc1 .Lstg_y_6
	s_waitcnt lgkmcnt(0)
	s_barrier
.Lstg_y_6:
	v_add_u32_e32 v133, s9, v199
	ds_read_b128 v[64:67], v133
	ds_read_b128 v[68:71], v133 offset:32
	ds_read_b128 v[72:75], v133 offset:4608
	ds_read_b128 v[76:79], v133 offset:4640
	ds_read_b128 v[134:137], v133 offset:64
	ds_read_b128 v[138:141], v133 offset:96
	ds_read_b128 v[142:145], v133 offset:4672
	ds_read_b128 v[146:149], v133 offset:4704
	s_waitcnt lgkmcnt(14)
	v_mfma_f32_32x32x16_bf16 v[16:31], v[124:127], v[48:51], v[16:31]
	s_waitcnt lgkmcnt(14)
	v_mfma_f32_32x32x16_bf16 v[0:15], v[128:131], v[48:51], v[0:15]
	v_mfma_f32_32x32x16_bf16 v[16:31], v[112:115], v[52:55], v[16:31]
	s_waitcnt lgkmcnt(13)
	v_mfma_f32_32x32x16_bf16 v[0:15], v[116:119], v[52:55], v[0:15]
	s_waitcnt lgkmcnt(12)
	v_mfma_f32_32x32x16_bf16 v[16:31], v[108:111], v[56:59], v[16:31]
	s_waitcnt lgkmcnt(10)
	v_mfma_f32_32x32x16_bf16 v[0:15], v[120:123], v[56:59], v[0:15]
	v_mfma_f32_32x32x16_bf16 v[16:31], v[100:103], v[60:63], v[16:31]
	s_waitcnt lgkmcnt(9)
	v_mfma_f32_32x32x16_bf16 v[0:15], v[104:107], v[60:63], v[0:15]
	s_waitcnt lgkmcnt(8)
	v_mfma_f32_32x32x16_bf16 v[48:63], v[64:67], v[80:83], v[32:47]
	s_waitcnt lgkmcnt(6)
	v_mfma_f32_32x32x16_bf16 v[32:47], v[72:75], v[80:83], v[32:47]
	v_mfma_f32_32x32x16_bf16 v[48:63], v[68:71], v[84:87], v[48:63]
	s_waitcnt lgkmcnt(5)
	v_mfma_f32_32x32x16_bf16 v[32:47], v[76:79], v[84:87], v[32:47]
	s_waitcnt lgkmcnt(4)
	v_mfma_f32_32x32x16_bf16 v[48:63], v[134:137], v[92:95], v[48:63]
	s_waitcnt lgkmcnt(2)
	v_mfma_f32_32x32x16_bf16 v[32:47], v[142:145], v[92:95], v[32:47]
	v_mfma_f32_32x32x16_bf16 v[48:63], v[138:141], v[88:91], v[48:63]
	s_waitcnt lgkmcnt(1)
	v_mfma_f32_32x32x16_bf16 v[32:47], v[146:149], v[88:91], v[32:47]
	ds_read_b128 v[104:107], v199 offset:27648
	ds_read_b128 v[96:99], v199 offset:27680
	ds_read_b128 v[108:111], v199 offset:32256
	ds_read_b128 v[100:103], v199 offset:32288
	ds_read_b128 v[92:95], v199 offset:27712
	ds_read_b128 v[84:87], v199 offset:27744
	ds_read_b128 v[88:91], v199 offset:32320
	ds_read_b128 v[80:83], v199 offset:32352
	s_nop 1
	v_max3_f32 v64, v48, v49, v50
	s_nop 0
	v_max3_f32 v65, v32, v33, v34
	v_max3_f32 v64, v64, v51, v52
	v_max3_f32 v65, v65, v35, v36
	v_max3_f32 v64, v64, v53, v54
	v_max3_f32 v65, v65, v37, v38
	v_max3_f32 v64, v64, v55, v56
	v_max3_f32 v65, v65, v39, v40
	v_max3_f32 v64, v64, v57, v58
	v_max3_f32 v65, v65, v41, v42
	v_max3_f32 v64, v64, v59, v60
	v_max3_f32 v65, v65, v43, v44
	v_max_f32_e32 v66, v47, v47
	v_max_f32_e32 v67, v63, v63
	v_max3_f32 v64, v64, v61, v62
	v_max3_f32 v65, v65, v45, v46
	v_max_f32_e32 v66, v67, v66
	v_max3_f32 v64, v64, v65, v66
	v_mov_b32_e32 v65, v64
	s_nop 1
	v_permlane32_swap_b32_e32 v64, v65
	v_max_f32_e32 v65, v65, v65
	v_max_f32_e32 v64, v64, v64
	v_max_f32_e32 v64, v64, v65
	s_cmp_eq_u32 s98, 0
	s_cbranch_scc1 .Lstg_x_7
	s_waitcnt lgkmcnt(0)
	s_barrier
.Lstg_x_7:
	v_cmp_lt_f32_e32 vcc, s68, v64
	s_cbranch_vccz .LBB0_344
	v_max_f32_e32 v64, v64, v64
	v_max_f32_e32 v66, 0, v64
	v_exp_f32_e64 v68, -v66
	v_add_f32_e32 v64, v195, v66
	v_xor_b32_e32 v64, 0x80000000, v64
	v_pk_add_f32 v[48:49], v[48:49], v[66:67] op_sel_hi:[1,0] neg_lo:[0,1] neg_hi:[0,1]
	v_pk_mul_f32 v[14:15], v[14:15], v[68:69] op_sel_hi:[1,0]
	v_pk_mul_f32 v[12:13], v[12:13], v[68:69] op_sel_hi:[1,0]
	v_pk_mul_f32 v[10:11], v[10:11], v[68:69] op_sel_hi:[1,0]
	v_pk_mul_f32 v[8:9], v[8:9], v[68:69] op_sel_hi:[1,0]
	v_pk_mul_f32 v[6:7], v[6:7], v[68:69] op_sel_hi:[1,0]
	v_pk_mul_f32 v[4:5], v[4:5], v[68:69] op_sel_hi:[1,0]
	v_pk_mul_f32 v[2:3], v[2:3], v[68:69] op_sel_hi:[1,0]
	v_pk_mul_f32 v[0:1], v[0:1], v[68:69] op_sel_hi:[1,0]
	v_pk_add_f32 v[32:33], v[32:33], v[66:67] op_sel_hi:[1,0] neg_lo:[0,1] neg_hi:[0,1]
	v_pk_add_f32 v[50:51], v[50:51], v[66:67] op_sel_hi:[1,0] neg_lo:[0,1] neg_hi:[0,1]
	v_pk_add_f32 v[34:35], v[34:35], v[66:67] op_sel_hi:[1,0] neg_lo:[0,1] neg_hi:[0,1]
	v_pk_add_f32 v[52:53], v[52:53], v[66:67] op_sel_hi:[1,0] neg_lo:[0,1] neg_hi:[0,1]
	v_pk_add_f32 v[36:37], v[36:37], v[66:67] op_sel_hi:[1,0] neg_lo:[0,1] neg_hi:[0,1]
	v_pk_add_f32 v[54:55], v[54:55], v[66:67] op_sel_hi:[1,0] neg_lo:[0,1] neg_hi:[0,1]
	v_pk_add_f32 v[38:39], v[38:39], v[66:67] op_sel_hi:[1,0] neg_lo:[0,1] neg_hi:[0,1]
	v_pk_add_f32 v[56:57], v[56:57], v[66:67] op_sel_hi:[1,0] neg_lo:[0,1] neg_hi:[0,1]
	v_pk_add_f32 v[40:41], v[40:41], v[66:67] op_sel_hi:[1,0] neg_lo:[0,1] neg_hi:[0,1]
	v_pk_add_f32 v[58:59], v[58:59], v[66:67] op_sel_hi:[1,0] neg_lo:[0,1] neg_hi:[0,1]
	v_pk_add_f32 v[42:43], v[42:43], v[66:67] op_sel_hi:[1,0] neg_lo:[0,1] neg_hi:[0,1]
	v_pk_add_f32 v[60:61], v[60:61], v[66:67] op_sel_hi:[1,0] neg_lo:[0,1] neg_hi:[0,1]
	v_pk_add_f32 v[44:45], v[44:45], v[66:67] op_sel_hi:[1,0] neg_lo:[0,1] neg_hi:[0,1]
	v_pk_add_f32 v[62:63], v[62:63], v[66:67] op_sel_hi:[1,0] neg_lo:[0,1] neg_hi:[0,1]
	v_pk_add_f32 v[46:47], v[46:47], v[66:67] op_sel_hi:[1,0] neg_lo:[0,1] neg_hi:[0,1]
	v_pk_mul_f32 v[30:31], v[30:31], v[68:69] op_sel_hi:[1,0]
	v_pk_mul_f32 v[28:29], v[28:29], v[68:69] op_sel_hi:[1,0]
	v_pk_mul_f32 v[26:27], v[26:27], v[68:69] op_sel_hi:[1,0]
	v_pk_mul_f32 v[24:25], v[24:25], v[68:69] op_sel_hi:[1,0]
	v_pk_mul_f32 v[22:23], v[22:23], v[68:69] op_sel_hi:[1,0]
	v_pk_mul_f32 v[20:21], v[20:21], v[68:69] op_sel_hi:[1,0]
	v_pk_mul_f32 v[18:19], v[18:19], v[68:69] op_sel_hi:[1,0]
	v_pk_mul_f32 v[16:17], v[16:17], v[68:69] op_sel_hi:[1,0]
	v_mul_f32_e32 v132, v132, v68
	v_mov_b32_e32 v65, v64
	v_mov_b32_e32 v66, v64
	v_mov_b32_e32 v67, v64
	v_mov_b32_e32 v68, v64
	v_mov_b32_e32 v69, v64
	v_mov_b32_e32 v70, v64
	v_mov_b32_e32 v71, v64
	v_mov_b32_e32 v72, v64
	v_mov_b32_e32 v73, v64
	v_mov_b32_e32 v74, v64
	v_mov_b32_e32 v75, v64
	v_mov_b32_e32 v76, v64
	v_mov_b32_e32 v77, v64
	v_mov_b32_e32 v78, v64
	v_mov_b32_e32 v79, v64
.LBB0_344:
	s_nop 0
	v_exp_f32_e32 v64, v48
	v_exp_f32_e32 v65, v32
	v_exp_f32_e32 v66, v49
	v_exp_f32_e32 v67, v33
	v_exp_f32_e32 v68, v50
	v_exp_f32_e32 v69, v34
	v_exp_f32_e32 v70, v51
	v_exp_f32_e32 v71, v35
	v_add_f32_e32 v32, v65, v64
	v_exp_f32_e32 v72, v52
	v_exp_f32_e32 v73, v36
	v_add_f32_e32 v32, 0, v32
	v_add_f32_e32 v33, v67, v66
	v_exp_f32_e32 v74, v53
	v_exp_f32_e32 v75, v37
	v_add_f32_e32 v32, v33, v32
	v_add_f32_e32 v33, v69, v68
	v_exp_f32_e32 v54, v54
	v_exp_f32_e32 v76, v38
	v_add_f32_e32 v32, v33, v32
	v_add_f32_e32 v33, v71, v70
	v_exp_f32_e32 v55, v55
	v_exp_f32_e32 v77, v39
	v_add_f32_e32 v32, v33, v32
	v_add_f32_e32 v33, v73, v72
	v_add_f32_e32 v32, v33, v32
	v_add_f32_e32 v33, v75, v74
	v_add_f32_e32 v32, v33, v32
	v_add_f32_e32 v33, v76, v54
	v_add_f32_e32 v32, v33, v32
	v_add_f32_e32 v33, v77, v55
	v_add_f32_e32 v50, v33, v32
	v_exp_f32_e32 v33, v56
	v_exp_f32_e32 v35, v40
	v_exp_f32_e32 v32, v57
	v_exp_f32_e32 v34, v41
	v_exp_f32_e32 v49, v58
	v_exp_f32_e32 v37, v42
	v_exp_f32_e32 v48, v59
	v_exp_f32_e32 v36, v43
	v_pk_add_f32 v[38:39], v[34:35], v[32:33]
	v_exp_f32_e32 v51, v60
	v_add_f32_e32 v39, v39, v50
	v_add_f32_e32 v40, v38, v39
	v_pk_add_f32 v[38:39], v[36:37], v[48:49]
	v_exp_f32_e32 v50, v61
	v_add_f32_e32 v39, v39, v40
	v_add_f32_e32 v56, v38, v39
	v_exp_f32_e32 v39, v44
	v_exp_f32_e32 v38, v45
	v_exp_f32_e32 v53, v62
	v_exp_f32_e32 v41, v46
	v_exp_f32_e32 v52, v63
	v_exp_f32_e32 v40, v47
	v_pk_add_f32 v[42:43], v[38:39], v[50:51]
	s_nop 0
	v_add_f32_e32 v43, v43, v56
	v_add_f32_e32 v44, v42, v43
	v_pk_add_f32 v[42:43], v[40:41], v[52:53]
	s_nop 0
	v_add_f32_e32 v43, v43, v44
	v_add_f32_e32 v42, v42, v43
	v_add_f32_e32 v56, v132, v42
	v_pk_mov_b32 v[32:33], v[32:33], v[32:33] op_sel:[1,0]
	v_pk_mov_b32 v[34:35], v[34:35], v[34:35] op_sel:[1,0]
	v_pk_mov_b32 v[36:37], v[36:37], v[36:37] op_sel:[1,0]
	v_cvt_pk_bf16_f32 v42, v32, v33
	v_pk_mov_b32 v[32:33], v[48:49], v[48:49] op_sel:[1,0]
	v_cvt_pk_bf16_f32 v34, v34, v35
	v_cvt_pk_bf16_f32 v35, v36, v37
	v_pk_mov_b32 v[36:37], v[38:39], v[38:39] op_sel:[1,0]
	v_pk_mov_b32 v[38:39], v[40:41], v[40:41] op_sel:[1,0]
	v_cvt_pk_bf16_f32 v43, v32, v33
	v_pk_mov_b32 v[32:33], v[50:51], v[50:51] op_sel:[1,0]
	v_cvt_pk_bf16_f32 v36, v36, v37
	v_cvt_pk_bf16_f32 v37, v38, v39
	v_cvt_pk_bf16_f32 v38, v65, v67
	v_cvt_pk_bf16_f32 v39, v69, v71
	v_cvt_pk_bf16_f32 v44, v32, v33
	v_pk_mov_b32 v[32:33], v[52:53], v[52:53] op_sel:[1,0]
	v_cvt_pk_bf16_f32 v40, v73, v75
	v_cvt_pk_bf16_f32 v41, v76, v77
	v_cvt_pk_bf16_f32 v45, v32, v33
	v_cvt_pk_bf16_f32 v46, v64, v66
	v_cvt_pk_bf16_f32 v47, v68, v70
	v_cvt_pk_bf16_f32 v48, v72, v74
	v_cvt_pk_bf16_f32 v49, v54, v55
	s_cmp_lg_u32 s98, 0
	s_cbranch_scc1 .Lstg_y_8
	s_waitcnt lgkmcnt(0)
	s_barrier
.Lstg_y_8:
	s_waitcnt lgkmcnt(5)
	s_nop 0
	v_mfma_f32_32x32x16_bf16 v[0:15], v[108:111], v[46:49], v[0:15]
	ds_bpermute_b32 v32, v218, v56
	s_waitcnt lgkmcnt(0)
	v_add_f32_e32 v32, v56, v32
	v_div_scale_f32 v33, s[8:9], v32, v32, 1.0
	v_mfma_f32_32x32x16_bf16 v[16:31], v[104:107], v[46:49], v[16:31]
	v_mfma_f32_32x32x16_bf16 v[0:15], v[100:103], v[42:45], v[0:15]
	v_mfma_f32_32x32x16_bf16 v[16:31], v[96:99], v[42:45], v[16:31]
	v_rcp_f32_e32 v42, v33
	v_mfma_f32_32x32x16_bf16 v[0:15], v[88:91], v[38:41], v[0:15]
	v_mfma_f32_32x32x16_bf16 v[16:31], v[92:95], v[38:41], v[16:31]
	v_fma_f32 v38, -v33, v42, 1.0
	v_fmac_f32_e32 v42, v38, v42
	v_div_scale_f32 v38, vcc, 1.0, v32, 1.0
	v_mul_f32_e32 v39, v38, v42
	v_fma_f32 v40, -v33, v39, v38
	v_fmac_f32_e32 v39, v40, v42
	v_mfma_f32_32x32x16_bf16 v[0:15], v[80:83], v[34:37], v[0:15]
	v_fma_f32 v33, -v33, v39, v38
	v_div_fmas_f32 v33, v33, v42, v39
	v_div_fixup_f32 v40, v33, v32, 1.0
	v_mfma_f32_32x32x16_bf16 v[16:31], v[84:87], v[34:37], v[16:31]
	s_nop 7
	v_mul_f32_e64 v0, v0, v40
	v_mul_f32_e64 v1, v1, v40
	v_mul_f32_e64 v2, v2, v40
	v_mul_f32_e64 v3, v3, v40
	v_pk_mul_f32 v[32:33], v[16:17], v[40:41] op_sel_hi:[1,0]
	v_pk_mul_f32 v[16:17], v[0:1], v[0:1]
	v_pk_mul_f32 v[34:35], v[18:19], v[40:41] op_sel_hi:[1,0]
	v_pk_fma_f32 v[42:43], v[32:33], v[32:33], v[16:17]
	v_pk_mul_f32 v[16:17], v[2:3], v[2:3]
	v_pk_mul_f32 v[36:37], v[20:21], v[40:41] op_sel_hi:[1,0]
	v_pk_fma_f32 v[44:45], v[34:35], v[34:35], v[16:17]
	v_pk_mul_f32 v[16:17], v[4:5], v[40:41] op_sel_hi:[1,0]
	v_pk_mul_f32 v[18:19], v[6:7], v[40:41] op_sel_hi:[1,0]
	v_pk_mul_f32 v[4:5], v[16:17], v[16:17]
	v_pk_mul_f32 v[38:39], v[22:23], v[40:41] op_sel_hi:[1,0]
	v_pk_fma_f32 v[46:47], v[36:37], v[36:37], v[4:5]
	v_pk_mul_f32 v[4:5], v[18:19], v[18:19]
	v_pk_mul_f32 v[20:21], v[24:25], v[40:41] op_sel_hi:[1,0]
	v_pk_fma_f32 v[48:49], v[38:39], v[38:39], v[4:5]
	v_pk_mul_f32 v[4:5], v[8:9], v[40:41] op_sel_hi:[1,0]
	v_pk_mul_f32 v[22:23], v[26:27], v[40:41] op_sel_hi:[1,0]
	v_pk_mul_f32 v[6:7], v[4:5], v[4:5]
	v_pk_mul_f32 v[24:25], v[28:29], v[40:41] op_sel_hi:[1,0]
	v_pk_fma_f32 v[50:51], v[20:21], v[20:21], v[6:7]
	v_pk_mul_f32 v[6:7], v[10:11], v[40:41] op_sel_hi:[1,0]
	s_nop 0
	v_pk_mul_f32 v[8:9], v[6:7], v[6:7]
	s_nop 0
	v_pk_fma_f32 v[26:27], v[22:23], v[22:23], v[8:9]
	v_pk_mul_f32 v[8:9], v[12:13], v[40:41] op_sel_hi:[1,0]
	v_pk_mul_f32 v[12:13], v[30:31], v[40:41] op_sel_hi:[1,0]
	v_add_f32_e32 v30, v42, v43
	v_add_f32_e32 v30, v44, v30
	v_add_f32_e32 v30, v45, v30
	v_add_f32_e32 v30, v46, v30
	v_add_f32_e32 v30, v47, v30
	v_add_f32_e32 v30, v48, v30
	v_add_f32_e32 v30, v49, v30
	v_add_f32_e32 v30, v50, v30
	v_add_f32_e32 v30, v51, v30
	v_pk_mul_f32 v[10:11], v[8:9], v[8:9]
	v_add_f32_e32 v26, v26, v30
	v_pk_fma_f32 v[28:29], v[24:25], v[24:25], v[10:11]
	v_pk_mul_f32 v[10:11], v[14:15], v[40:41] op_sel_hi:[1,0]
	v_add_f32_e32 v26, v27, v26
	v_pk_mul_f32 v[14:15], v[10:11], v[10:11]
	v_add_f32_e32 v26, v28, v26
	v_pk_fma_f32 v[14:15], v[12:13], v[12:13], v[14:15]
	v_add_f32_e32 v26, v29, v26
	v_add_f32_e32 v14, v14, v26
	v_add_f32_e32 v14, v15, v14
	ds_bpermute_b32 v15, v218, v14
	s_and_saveexec_b64 s[8:9], s[6:7]
	s_cbranch_execz .LBB0_346
	s_lshl_b32 s18, s75, 2
	s_add_u32 s18, s11, s18
	v_readlane_b32 s19, v242, 36
	s_addc_u32 s19, s19, 0
	s_lshl_b32 s33, s74, 2
	s_add_u32 s33, s18, s33
	s_addc_u32 s38, s19, 0
	s_lshl_b64 s[18:19], s[14:15], 2
	s_add_u32 s18, s33, s18
	s_addc_u32 s19, s38, s19
	v_lshlrev_b32_e32 v26, 2, v170
	s_waitcnt lgkmcnt(0)
	v_add_f32_e32 v14, v14, v15
	global_atomic_add_f32 v26, v14, s[18:19]

.LBB0_354:
	s_or_b64 exec, exec, s[42:43]
	global_load_dwordx4 v[52:55], v[192:193], off offset:128
	s_waitcnt vmcnt(1)
	ds_write_b128 v220, v[48:51] offset:13312
	s_and_saveexec_b64 s[42:43], s[4:5]
	ds_write_b128 v187, v[104:107] offset:13312
	s_or_b64 exec, exec, s[42:43]
	v_add_u32_e32 v58, 0xc000, v198
	s_waitcnt vmcnt(0)
	ds_write2_b64 v58, v[52:53], v[54:55] offset1:2
	v_mov_b32_e32 v189, v173
	v_lshl_add_u64 v[146:147], s[8:9], 0, v[188:189]
	v_add_co_u32_e32 v48, vcc, 0x6000, v146
	s_waitcnt lgkmcnt(0)
	s_barrier
	s_nop 0
	v_addc_co_u32_e32 v49, vcc, 0, v147, vcc
	global_load_dwordx4 v[48:51], v[48:49], off
	ds_read_b128 v[72:75], v208
	ds_read_b128 v[64:67], v208 offset:32
	ds_read_b128 v[68:71], v208 offset:6656
	ds_read_b128 v[56:59], v208 offset:64
	ds_read_b128 v[60:63], v208 offset:6688
	ds_read_b128 v[52:55], v208 offset:6720
	s_and_saveexec_b64 s[8:9], s[4:5]
	s_cbranch_execz .LBB0_358
	s_mov_b64 s[18:19], 0x6000
	v_lshl_add_u64 v[104:105], v[146:147], 0, s[18:19]
	v_add_co_u32_e32 v104, vcc, 0x2000, v104
	s_nop 1
	v_addc_co_u32_e32 v105, vcc, 0, v105, vcc
	global_load_dwordx4 v[104:107], v[104:105], off
.LBB0_358:
	s_or_b64 exec, exec, s[8:9]
	v_mov_b32_e32 v135, v134
	v_pk_mul_f32 v[24:25], v[24:25], v[134:135]
	v_pk_mul_f32 v[26:27], v[26:27], v[134:135]
	v_pk_mul_f32 v[24:25], v[24:25], v[82:83]
	v_pk_mul_f32 v[26:27], v[26:27], v[80:81]
	v_cvt_pk_bf16_f32 v82, v24, v25
	v_add_u32_e32 v24, s0, v148
	v_ashrrev_i32_e32 v24, 6, v24
	v_cvt_f32_i32_e32 v24, v24
	v_cvt_pk_bf16_f32 v83, v26, v27
	v_and_b32_e32 v25, 63, v148
	v_cvt_f32_ubyte0_e32 v25, v25
	v_mul_f32_e32 v26, 0.15915494, v24
	v_cos_f32_e32 v146, v26
	v_sin_f32_e32 v158, v26
	v_mul_f32_e32 v26, v169, v24
	v_mul_f32_e32 v26, 0.15915494, v26
	v_cos_f32_e32 v147, v26
	v_sin_f32_e32 v159, v26
	v_mul_f32_e32 v26, v200, v24
	v_mul_f32_e32 v26, 0.15915494, v26
	v_cos_f32_e32 v148, v26
	v_sin_f32_e32 v162, v26
	v_mul_f32_e32 v26, v201, v24
	v_mul_f32_e32 v26, 0.15915494, v26
	v_cos_f32_e32 v149, v26
	v_sin_f32_e32 v163, v26
	v_mul_f32_e32 v26, v202, v24
	v_mul_f32_e32 v26, 0.15915494, v26
	v_cos_f32_e32 v152, v26
	v_sin_f32_e32 v190, v26
	v_mul_f32_e32 v26, v203, v24
	v_mul_f32_e32 v26, 0.15915494, v26
	v_cos_f32_e32 v153, v26
	v_sin_f32_e32 v191, v26
	v_mul_f32_e32 v26, v204, v24
	v_mul_f32_e32 v24, v205, v24
	v_mul_f32_e32 v24, 0.15915494, v24
	v_pk_mul_f32 v[30:31], v[30:31], v[134:135]
	v_cos_f32_e32 v151, v24
	v_sin_f32_e32 v195, v24
	v_mul_f32_e32 v24, 0.15915494, v25
	v_pk_mul_f32 v[30:31], v[30:31], v[142:143]
	v_cos_f32_e32 v142, v24
	v_sin_f32_e32 v160, v24
	v_mul_f32_e32 v24, v169, v25
	v_mul_f32_e32 v24, 0.15915494, v24
	v_cos_f32_e32 v143, v24
	v_sin_f32_e32 v161, v24
	v_mul_f32_e32 v24, v200, v25
	v_pk_mul_f32 v[28:29], v[28:29], v[134:135]
	v_mul_f32_e32 v24, 0.15915494, v24
	v_pk_mul_f32 v[28:29], v[28:29], v[144:145]
	v_cos_f32_e32 v144, v24
	v_sin_f32_e32 v164, v24
	v_mul_f32_e32 v24, v201, v25
	v_mul_f32_e32 v24, 0.15915494, v24
	v_cos_f32_e32 v145, v24
	v_sin_f32_e32 v165, v24
	v_mul_f32_e32 v24, v202, v25
	v_mul_f32_e32 v24, 0.15915494, v24
	v_cos_f32_e32 v154, v24
	v_sin_f32_e32 v166, v24
	v_mul_f32_e32 v24, v203, v25
	v_mul_f32_e32 v24, 0.15915494, v24
	v_cos_f32_e32 v155, v24
	v_sin_f32_e32 v167, v24
	v_mul_f32_e32 v24, v204, v25
	v_mul_f32_e32 v24, 0.15915494, v24
	v_cos_f32_e32 v156, v24
	v_sin_f32_e32 v196, v24
	v_mul_f32_e32 v24, v205, v25
	v_pk_mul_f32 v[20:21], v[20:21], v[134:135]
	v_pk_mul_f32 v[22:23], v[22:23], v[134:135]
	v_pk_mul_f32 v[16:17], v[16:17], v[134:135]
	v_pk_mul_f32 v[18:19], v[18:19], v[134:135]
	v_cvt_pk_bf16_f32 v80, v28, v29
	v_cvt_pk_bf16_f32 v81, v30, v31
	v_mul_f32_e32 v26, 0.15915494, v26
	v_mul_f32_e32 v24, 0.15915494, v24
	v_pk_mul_f32 v[20:21], v[20:21], v[140:141]
	v_pk_mul_f32 v[22:23], v[22:23], v[138:139]
	v_pk_mul_f32 v[16:17], v[16:17], v[86:87]
	v_pk_mul_f32 v[18:19], v[18:19], v[84:85]
	v_cos_f32_e32 v150, v26
	v_sin_f32_e32 v194, v26
	v_cos_f32_e32 v157, v24
	v_sin_f32_e32 v197, v24
	v_cvt_pk_bf16_f32 v84, v20, v21
	v_cvt_pk_bf16_f32 v85, v22, v23
	v_cvt_pk_bf16_f32 v86, v16, v17
	v_cvt_pk_bf16_f32 v87, v18, v19
	s_waitcnt lgkmcnt(5)
	v_mfma_f32_32x32x16_bf16 v[16:31], v[72:75], v[80:83], v[0:15]
	v_mul_f32_e64 v32, v32, v134
	v_mul_f32_e64 v33, v33, v135
	v_mul_f32_e64 v36, v36, v134
	v_mul_f32_e64 v37, v37, v135
	v_mul_f32_e64 v32, v32, v78
	v_mul_f32_e64 v33, v33, v79
	v_pk_mul_f32 v[44:45], v[44:45], v[134:135]
	v_pk_mul_f32 v[36:37], v[36:37], v[94:95]
	v_cvt_pk_bf16_f32 v94, v32, v33
	v_pk_mul_f32 v[32:33], v[158:159], v[136:137]
	s_waitcnt lgkmcnt(3)
	v_mfma_f32_32x32x16_bf16 v[0:15], v[68:71], v[80:83], v[0:15]
	v_cmp_eq_u32_e32 vcc, 0, v219
	v_mul_f32_e64 v44, v44, v98
	v_mul_f32_e64 v45, v45, v99
	v_mul_f32_e64 v42, v42, v134
	v_mul_f32_e64 v43, v43, v135
	v_cndmask_b32_e64 v33, v33, -v33, vcc
	v_cndmask_b32_e64 v32, v32, -v32, vcc
	v_pk_mul_f32 v[46:47], v[46:47], v[134:135]
	v_pk_mul_f32 v[40:41], v[40:41], v[134:135]
	v_mfma_f32_32x32x16_bf16 v[16:31], v[64:67], v[84:87], v[16:31]
	v_mul_f32_e64 v42, v42, v88
	v_mul_f32_e64 v43, v43, v89
	v_cvt_pk_bf16_f32 v88, v44, v45
	v_mul_f32_e64 v34, v34, v134
	v_mul_f32_e64 v35, v35, v135
	v_pk_fma_f32 v[44:45], v[146:147], v[128:129], v[32:33]
	v_pk_mul_f32 v[32:33], v[162:163], v[132:133]
	v_pk_mul_f32 v[46:47], v[46:47], v[96:97]
	v_pk_mul_f32 v[40:41], v[40:41], v[90:91]
	s_waitcnt lgkmcnt(1)
	v_mfma_f32_32x32x16_bf16 v[0:15], v[60:63], v[84:87], v[0:15]
	v_mul_f32_e64 v34, v34, v76
	v_mul_f32_e64 v35, v35, v77
	v_cndmask_b32_e64 v33, v33, -v33, vcc
	v_cndmask_b32_e64 v32, v32, -v32, vcc
	v_cvt_pk_bf16_f32 v89, v46, v47
	v_cvt_pk_bf16_f32 v90, v40, v41
	v_cvt_pk_bf16_f32 v91, v42, v43
	v_cvt_pk_bf16_f32 v95, v34, v35
	v_pk_fma_f32 v[46:47], v[148:149], v[122:123], v[32:33]
	ds_read_b128 v[32:35], v208 offset:96
	v_pk_mul_f32 v[38:39], v[38:39], v[134:135]
	v_mfma_f32_32x32x16_bf16 v[16:31], v[56:59], v[88:91], v[16:31]
	v_mul_f32_e64 v38, v38, v92
	v_mul_f32_e64 v39, v39, v93
	v_cvt_pk_bf16_f32 v92, v36, v37
	v_mul_f32_e64 v36, v190, v130
	v_mul_f32_e64 v37, v191, v131
	v_cvt_pk_bf16_f32 v93, v38, v39
	v_cndmask_b32_e64 v37, v37, -v37, vcc
	v_cndmask_b32_e64 v36, v36, -v36, vcc
	v_cvt_pk_bf16_f32 v96, v44, v45
	s_waitcnt lgkmcnt(1)
	v_mfma_f32_32x32x16_bf16 v[0:15], v[52:55], v[88:91], v[0:15]
	v_fma_f32 v52, v152, v118, v36
	v_fma_f32 v53, v153, v119, v37
	v_mul_f32_e64 v36, v194, v126
	v_mul_f32_e64 v37, v195, v127
	v_mul_f32_e64 v44, v160, v124
	v_mul_f32_e64 v45, v161, v125
	v_cndmask_b32_e64 v55, v37, -v37, vcc
	v_cndmask_b32_e64 v54, v36, -v36, vcc
	ds_read_b128 v[36:39], v208 offset:6752
	ds_read_b128 v[40:43], v208 offset:128
	v_cvt_pk_bf16_f32 v97, v46, v47
	s_waitcnt lgkmcnt(2)
	v_mfma_f32_32x32x16_bf16 v[16:31], v[32:35], v[92:95], v[16:31]
	v_fma_f32 v32, v150, v112, v54
	v_fma_f32 v33, v151, v113, v55
	v_cvt_pk_bf16_f32 v98, v52, v53
	v_cvt_pk_bf16_f32 v99, v32, v33
	ds_read_b128 v[32:35], v208 offset:160
	v_pk_mul_f32 v[54:55], v[196:197], v[114:115]
	s_waitcnt lgkmcnt(2)
	v_mfma_f32_32x32x16_bf16 v[0:15], v[36:39], v[92:95], v[0:15]
	v_cndmask_b32_e64 v37, v45, -v45, vcc
	v_cndmask_b32_e64 v36, v44, -v44, vcc
	v_fma_f32 v44, v142, v110, v36
	v_fma_f32 v45, v143, v111, v37
	v_mul_f32_e64 v36, v164, v120
	v_mul_f32_e64 v37, v165, v121
	v_cndmask_b32_e64 v47, v37, -v37, vcc
	v_cndmask_b32_e64 v46, v36, -v36, vcc
	ds_read_b128 v[36:39], v208 offset:6784
	s_waitcnt lgkmcnt(2)
	v_mfma_f32_32x32x16_bf16 v[16:31], v[40:43], v[96:99], v[16:31]
	v_mul_f32_e64 v40, v166, v116
	v_mul_f32_e64 v41, v167, v117
	v_fma_f32 v46, v144, v108, v46
	v_fma_f32 v47, v145, v109, v47
	v_cndmask_b32_e64 v41, v41, -v41, vcc
	v_cndmask_b32_e64 v40, v40, -v40, vcc
	v_pk_fma_f32 v[52:53], v[154:155], v[102:103], v[40:41]
	ds_read_b128 v[40:43], v208 offset:6816
	v_cvt_pk_bf16_f32 v102, v52, v53
	s_waitcnt lgkmcnt(1)
	v_mfma_f32_32x32x16_bf16 v[0:15], v[36:39], v[96:99], v[0:15]
	v_cndmask_b32_e64 v37, v55, -v55, vcc
	v_cndmask_b32_e64 v36, v54, -v54, vcc
	global_load_dwordx4 v[52:55], v[192:193], off offset:256
	v_fma_f32 v36, v156, v100, v36
	v_fma_f32 v37, v157, v101, v37
	v_cvt_pk_bf16_f32 v100, v44, v45
	v_cvt_pk_bf16_f32 v101, v46, v47
	v_cvt_pk_bf16_f32 v103, v36, v37
	s_nop 1
	v_mfma_f32_32x32x16_bf16 v[16:31], v[32:35], v[100:103], v[16:31]
	s_waitcnt lgkmcnt(0)
	v_mfma_f32_32x32x16_bf16 v[0:15], v[40:43], v[100:103], v[0:15]
	ds_read_b128 v[64:67], v209 offset:39936
	ds_read_b128 v[68:71], v209 offset:39968
	ds_read_b128 v[72:75], v209 offset:44544
	ds_read_b128 v[76:79], v209 offset:44576
	ds_read_b128 v[108:111], v209 offset:40000
	ds_read_b128 v[112:115], v209 offset:40032
	ds_read_b128 v[116:119], v209 offset:44608
	ds_read_b128 v[56:59], v209 offset:44640
	s_nop 1
	v_max3_f32 v32, v16, v17, v18
	s_nop 0
	v_max3_f32 v33, v0, v1, v2
	v_max3_f32 v32, v32, v19, v20
	v_max3_f32 v33, v33, v3, v4
	v_max3_f32 v32, v32, v21, v22
	v_max3_f32 v33, v33, v5, v6
	v_max3_f32 v32, v32, v23, v24
	v_max3_f32 v33, v33, v7, v8
	v_max3_f32 v32, v32, v25, v26
	v_max3_f32 v33, v33, v9, v10
	v_max3_f32 v32, v32, v27, v28
	v_max3_f32 v33, v33, v11, v12
	v_max_f32_e32 v34, v15, v15
	v_max_f32_e32 v35, v31, v31
	v_max3_f32 v32, v32, v29, v30
	v_max3_f32 v33, v33, v13, v14
	v_max_f32_e32 v34, v35, v34
	v_max3_f32 v32, v32, v33, v34
	v_mov_b32_e32 v33, v32
	s_nop 1
	v_permlane32_swap_b32_e32 v32, v33
	v_max_f32_e32 v33, v33, v33
	v_max_f32_e32 v32, v32, v32
	v_max_f32_e32 v33, v32, v33
	s_cmp_eq_u32 s98, 0
	s_cbranch_scc1 .Lstg_x_9
	s_waitcnt lgkmcnt(0)
	s_barrier
.Lstg_x_9:
	v_sub_f32_e32 v0, v0, v33
	v_sub_f32_e32 v32, v7, v33
	v_sub_f32_e32 v7, v16, v33
	v_sub_f32_e32 v1, v1, v33
	v_sub_f32_e32 v34, v8, v33
	v_sub_f32_e32 v37, v11, v33
	v_sub_f32_e32 v8, v17, v33
	v_sub_f32_e32 v11, v20, v33
	v_sub_f32_e32 v20, v28, v33
	v_exp_f32_e32 v28, v7
	v_exp_f32_e32 v60, v0
	v_sub_f32_e32 v39, v13, v33
	v_sub_f32_e32 v40, v14, v33
	v_sub_f32_e32 v13, v22, v33
	v_sub_f32_e32 v14, v23, v33
	v_sub_f32_e32 v22, v29, v33
	v_sub_f32_e32 v23, v30, v33
	v_exp_f32_e32 v29, v8
	v_exp_f32_e32 v30, v1
	v_sub_f32_e32 v2, v2, v33
	v_sub_f32_e32 v35, v9, v33
	v_sub_f32_e32 v9, v18, v33
	v_sub_f32_e32 v3, v3, v33
	v_sub_f32_e32 v36, v10, v33
	v_sub_f32_e32 v41, v15, v33
	v_sub_f32_e32 v10, v19, v33
	v_sub_f32_e32 v15, v24, v33
	v_sub_f32_e32 v24, v31, v33
	v_add_f32_e32 v0, v28, v60
	v_exp_f32_e32 v31, v9
	v_exp_f32_e32 v61, v2
	v_sub_f32_e32 v4, v4, v33
	v_sub_f32_e32 v5, v5, v33
	v_sub_f32_e32 v38, v12, v33
	v_sub_f32_e32 v12, v21, v33
	v_add_f32_e32 v0, 0, v0
	v_add_f32_e32 v1, v29, v30
	v_exp_f32_e32 v62, v10
	v_exp_f32_e32 v63, v3
	v_add_f32_e32 v7, v1, v0
	v_exp_f32_e32 v1, v11
	v_exp_f32_e32 v3, v4
	v_exp_f32_e32 v0, v12
	v_exp_f32_e32 v2, v5
	v_add_f32_e32 v8, v31, v61
	v_add_f32_e32 v4, v8, v7
	v_add_f32_e32 v5, v62, v63
	v_sub_f32_e32 v6, v6, v33
	v_add_f32_e32 v7, v5, v4
	v_pk_add_f32 v[4:5], v[0:1], v[2:3]
	v_exp_f32_e32 v9, v6
	v_add_f32_e32 v5, v5, v7
	v_exp_f32_e32 v7, v13
	v_exp_f32_e32 v6, v14
	v_exp_f32_e32 v8, v32
	v_sub_f32_e32 v16, v25, v33
	v_pk_mov_b32 v[10:11], v[0:1], v[0:1] op_sel:[1,0]
	v_pk_mov_b32 v[12:13], v[2:3], v[2:3] op_sel:[1,0]
	v_add_f32_e32 v2, v4, v5
	v_pk_add_f32 v[0:1], v[6:7], v[8:9]
	v_exp_f32_e32 v3, v15
	v_add_f32_e32 v1, v1, v2
	v_exp_f32_e32 v5, v34
	v_exp_f32_e32 v2, v16
	v_exp_f32_e32 v4, v35
	v_sub_f32_e32 v17, v26, v33
	v_sub_f32_e32 v18, v27, v33
	v_add_f32_e32 v14, v0, v1
	v_pk_add_f32 v[0:1], v[2:3], v[4:5]
	v_exp_f32_e32 v15, v17
	v_add_f32_e32 v1, v1, v14
	v_exp_f32_e32 v17, v36
	v_exp_f32_e32 v14, v18
	v_exp_f32_e32 v16, v37
	v_pk_mov_b32 v[18:19], v[2:3], v[2:3] op_sel:[1,0]
	v_add_f32_e32 v2, v0, v1
	v_exp_f32_e32 v3, v20
	v_pk_add_f32 v[0:1], v[14:15], v[16:17]
	v_exp_f32_e32 v21, v38
	v_add_f32_e32 v1, v1, v2
	v_exp_f32_e32 v2, v22
	v_exp_f32_e32 v20, v39
	v_add_f32_e32 v22, v0, v1
	v_exp_f32_e32 v23, v23
	v_exp_f32_e32 v25, v40
	v_pk_add_f32 v[0:1], v[2:3], v[20:21]
	v_pk_mov_b32 v[26:27], v[2:3], v[2:3] op_sel:[1,0]
	v_add_f32_e32 v1, v1, v22
	v_exp_f32_e32 v22, v24
	v_exp_f32_e32 v24, v41
	v_add_f32_e32 v2, v0, v1
	v_pk_mov_b32 v[6:7], v[6:7], v[6:7] op_sel:[1,0]
	v_pk_mov_b32 v[8:9], v[8:9], v[8:9] op_sel:[1,0]
	v_pk_add_f32 v[0:1], v[22:23], v[24:25]
	v_pk_mov_b32 v[4:5], v[4:5], v[4:5] op_sel:[1,0]
	v_add_f32_e32 v1, v1, v2
	v_add_f32_e32 v32, v0, v1
	v_pk_add_f32 v[190:191], v[32:33], 0 op_sel_hi:[1,0]
	v_pk_mov_b32 v[14:15], v[14:15], v[14:15] op_sel:[1,0]
	v_xor_b32_e32 v32, 0x80000000, v191
	v_pk_mov_b32 v[16:17], v[16:17], v[16:17] op_sel:[1,0]
	v_pk_mov_b32 v[20:21], v[20:21], v[20:21] op_sel:[1,0]
	v_pk_mov_b32 v[22:23], v[22:23], v[22:23] op_sel:[1,0]
	v_pk_mov_b32 v[24:25], v[24:25], v[24:25] op_sel:[1,0]
	v_mov_b32_e32 v33, v32
	v_mov_b32_e32 v34, v32
	v_mov_b32_e32 v35, v32
	v_mov_b32_e32 v36, v32
	v_mov_b32_e32 v37, v32
	v_mov_b32_e32 v38, v32
	v_mov_b32_e32 v39, v32
	v_mov_b32_e32 v40, v32
	v_mov_b32_e32 v41, v32
	v_mov_b32_e32 v42, v32
	v_mov_b32_e32 v43, v32
	v_mov_b32_e32 v44, v32
	v_mov_b32_e32 v45, v32
	v_mov_b32_e32 v46, v32
	v_mov_b32_e32 v47, v32
	v_cvt_pk_bf16_f32 v0, v28, v29
	v_cvt_pk_bf16_f32 v1, v31, v62
	v_cvt_pk_bf16_f32 v2, v10, v11
	v_cvt_pk_bf16_f32 v3, v6, v7
	v_cvt_pk_bf16_f32 v120, v18, v19
	v_cvt_pk_bf16_f32 v121, v14, v15
	v_cvt_pk_bf16_f32 v122, v26, v27
	v_cvt_pk_bf16_f32 v123, v22, v23
	v_cvt_pk_bf16_f32 v124, v60, v30
	v_cvt_pk_bf16_f32 v125, v61, v63
	v_cvt_pk_bf16_f32 v126, v12, v13
	v_cvt_pk_bf16_f32 v127, v8, v9
	v_cvt_pk_bf16_f32 v128, v4, v5
	v_cvt_pk_bf16_f32 v129, v16, v17
	v_cvt_pk_bf16_f32 v130, v20, v21
	v_cvt_pk_bf16_f32 v131, v24, v25
	s_cmp_lg_u32 s98, 0
	s_cbranch_scc1 .Lstg_y_10
	s_waitcnt lgkmcnt(0)
	s_barrier
.Lstg_y_10:
	ds_read_b128 v[60:63], v208 offset:13312
	ds_read_b128 v[156:159], v208 offset:13344
	ds_read_b128 v[164:167], v208 offset:19968
	ds_read_b128 v[152:155], v208 offset:13376
	ds_read_b128 v[160:163], v208 offset:20000
	ds_read_b128 v[148:151], v208 offset:20032
	s_waitcnt lgkmcnt(13)
	v_mfma_f32_32x32x16_bf16 v[16:31], v[64:67], v[0:3], 0
	s_waitcnt vmcnt(1)
	ds_write_b128 v220, v[48:51] offset:26624
	s_waitcnt lgkmcnt(12)
	v_mfma_f32_32x32x16_bf16 v[0:15], v[72:75], v[0:3], 0
	v_mfma_f32_32x32x16_bf16 v[16:31], v[68:71], v[120:123], v[16:31]
	s_waitcnt lgkmcnt(11)
	v_mfma_f32_32x32x16_bf16 v[0:15], v[76:79], v[120:123], v[0:15]
	s_waitcnt lgkmcnt(10)
	v_mfma_f32_32x32x16_bf16 v[16:31], v[108:111], v[124:127], v[16:31]
	s_waitcnt lgkmcnt(8)
	v_mfma_f32_32x32x16_bf16 v[0:15], v[116:119], v[124:127], v[0:15]
	v_mfma_f32_32x32x16_bf16 v[16:31], v[112:115], v[128:131], v[16:31]
	s_waitcnt lgkmcnt(7)
	v_mfma_f32_32x32x16_bf16 v[0:15], v[56:59], v[128:131], v[0:15]
	s_and_saveexec_b64 s[8:9], s[4:5]
	ds_write_b128 v187, v[104:107] offset:26624
	s_or_b64 exec, exec, s[8:9]
	v_add_u32_e32 v187, 0x9c00, v198
	s_waitcnt vmcnt(0)
	ds_write2_b64 v187, v[52:53], v[54:55] offset1:2
	v_mad_u64_u32 v[194:195], s[8:9], s33, v217, v[182:183]
	s_or_b32 s8, s73, s44
	s_mov_b32 s9, s17
	s_lshl_b32 s3, s72, 6
	v_lshl_add_u64 v[196:197], v[184:185], 0, s[8:9]
	s_mov_b32 s42, 1
	s_mov_b32 s8, 0
	s_mov_b32 s33, 2
	s_mov_b32 s43, 2

.LBB0_363:
	s_or_b64 exec, exec, s[8:9]
	s_waitcnt lgkmcnt(7)
	v_mfma_f32_32x32x16_bf16 v[64:79], v[60:63], v[80:83], v[32:47]
	s_mul_i32 s8, s42, 0x3400
	v_add_u32_e32 v124, s8, v208
	ds_read_b128 v[108:111], v124 offset:96
	ds_read_b128 v[116:119], v124 offset:128
	s_waitcnt lgkmcnt(7)
	v_mfma_f32_32x32x16_bf16 v[48:63], v[164:167], v[80:83], v[32:47]
	v_mfma_f32_32x32x16_bf16 v[64:79], v[156:159], v[84:87], v[64:79]
	s_waitcnt lgkmcnt(5)
	v_mfma_f32_32x32x16_bf16 v[48:63], v[160:163], v[84:87], v[48:63]
	v_mfma_f32_32x32x16_bf16 v[64:79], v[152:155], v[88:91], v[64:79]
	s_waitcnt lgkmcnt(4)
	v_mfma_f32_32x32x16_bf16 v[48:63], v[148:151], v[88:91], v[48:63]
	s_waitcnt lgkmcnt(1)
	v_mfma_f32_32x32x16_bf16 v[64:79], v[108:111], v[92:95], v[64:79]
	ds_read_b128 v[108:111], v124 offset:6752
	ds_read_b128 v[120:123], v124 offset:160
	s_waitcnt lgkmcnt(1)
	v_mfma_f32_32x32x16_bf16 v[48:63], v[108:111], v[92:95], v[48:63]
	v_mfma_f32_32x32x16_bf16 v[64:79], v[116:119], v[96:99], v[64:79]
	ds_read_b128 v[108:111], v124 offset:6784
	ds_read_b128 v[116:119], v124 offset:6816
	s_waitcnt lgkmcnt(1)
	v_mfma_f32_32x32x16_bf16 v[48:63], v[108:111], v[96:99], v[48:63]
	global_load_dwordx4 v[108:111], v[196:197], off
	v_mfma_f32_32x32x16_bf16 v[64:79], v[120:123], v[100:103], v[64:79]
	s_waitcnt lgkmcnt(0)
	v_mfma_f32_32x32x16_bf16 v[48:63], v[116:119], v[100:103], v[48:63]
	s_and_b32 s72, 1, s33
	s_cselect_b32 s8, 0, 0x2400
	v_add_u32_e32 v116, s8, v209
	ds_read_b128 v[140:143], v116 offset:39936
	ds_read_b128 v[128:131], v116 offset:39968
	ds_read_b128 v[144:147], v116 offset:44544
	ds_read_b128 v[132:135], v116 offset:44576
	ds_read_b128 v[124:127], v116 offset:40000
	ds_read_b128 v[120:123], v116 offset:40032
	ds_read_b128 v[136:139], v116 offset:44608
	ds_read_b128 v[116:119], v116 offset:44640
	v_max3_f32 v148, v64, v65, v66
	v_max3_f32 v149, v48, v49, v50
	v_max3_f32 v148, v148, v67, v68
	v_max3_f32 v149, v149, v51, v52
	v_max3_f32 v148, v148, v69, v70
	v_max3_f32 v149, v149, v53, v54
	v_max3_f32 v148, v148, v71, v72
	v_max3_f32 v149, v149, v55, v56
	v_max3_f32 v148, v148, v73, v74
	v_max3_f32 v149, v149, v57, v58
	v_max3_f32 v148, v148, v75, v76
	v_max3_f32 v149, v149, v59, v60
	v_max_f32_e32 v150, v63, v63
	v_max_f32_e32 v151, v79, v79
	v_max3_f32 v148, v148, v77, v78
	v_max3_f32 v149, v149, v61, v62
	v_max_f32_e32 v150, v151, v150
	v_max3_f32 v148, v148, v149, v150
	v_mov_b32_e32 v149, v148
	s_nop 1
	v_permlane32_swap_b32_e32 v148, v149
	v_max_f32_e32 v149, v149, v149
	v_max_f32_e32 v148, v148, v148
	v_max_f32_e32 v148, v148, v149
	s_cmp_eq_u32 s98, 0
	s_cbranch_scc1 .Lstg_x_11
	s_waitcnt lgkmcnt(0)
	s_barrier
.Lstg_x_11:
	v_cmp_lt_f32_e32 vcc, s68, v148
	s_cbranch_vccz .LBB0_365
	v_max_f32_e32 v32, v148, v148
	v_max_f32_e32 v32, 0, v32
	v_exp_f32_e64 v34, -v32
	v_pk_add_f32 v[64:65], v[64:65], v[32:33] op_sel_hi:[1,0] neg_lo:[0,1] neg_hi:[0,1]
	v_pk_add_f32 v[48:49], v[48:49], v[32:33] op_sel_hi:[1,0] neg_lo:[0,1] neg_hi:[0,1]
	v_pk_add_f32 v[66:67], v[66:67], v[32:33] op_sel_hi:[1,0] neg_lo:[0,1] neg_hi:[0,1]
	v_pk_mul_f32 v[14:15], v[14:15], v[34:35] op_sel_hi:[1,0]
	v_pk_mul_f32 v[12:13], v[12:13], v[34:35] op_sel_hi:[1,0]
	v_pk_mul_f32 v[10:11], v[10:11], v[34:35] op_sel_hi:[1,0]
	v_pk_mul_f32 v[8:9], v[8:9], v[34:35] op_sel_hi:[1,0]
	v_pk_mul_f32 v[6:7], v[6:7], v[34:35] op_sel_hi:[1,0]
	v_pk_mul_f32 v[4:5], v[4:5], v[34:35] op_sel_hi:[1,0]
	v_pk_mul_f32 v[2:3], v[2:3], v[34:35] op_sel_hi:[1,0]
	v_pk_mul_f32 v[0:1], v[0:1], v[34:35] op_sel_hi:[1,0]
	v_pk_mul_f32 v[30:31], v[30:31], v[34:35] op_sel_hi:[1,0]
	v_pk_mul_f32 v[28:29], v[28:29], v[34:35] op_sel_hi:[1,0]
	v_pk_mul_f32 v[26:27], v[26:27], v[34:35] op_sel_hi:[1,0]
	v_pk_mul_f32 v[24:25], v[24:25], v[34:35] op_sel_hi:[1,0]
	v_pk_mul_f32 v[22:23], v[22:23], v[34:35] op_sel_hi:[1,0]
	v_pk_mul_f32 v[20:21], v[20:21], v[34:35] op_sel_hi:[1,0]
	v_pk_mul_f32 v[18:19], v[18:19], v[34:35] op_sel_hi:[1,0]
	v_pk_mul_f32 v[16:17], v[16:17], v[34:35] op_sel_hi:[1,0]
	v_mov_b32_e32 v35, v32
	v_pk_add_f32 v[50:51], v[50:51], v[32:33] op_sel_hi:[1,0] neg_lo:[0,1] neg_hi:[0,1]
	v_pk_add_f32 v[68:69], v[68:69], v[32:33] op_sel_hi:[1,0] neg_lo:[0,1] neg_hi:[0,1]
	v_pk_add_f32 v[52:53], v[52:53], v[32:33] op_sel_hi:[1,0] neg_lo:[0,1] neg_hi:[0,1]
	v_pk_add_f32 v[70:71], v[70:71], v[32:33] op_sel_hi:[1,0] neg_lo:[0,1] neg_hi:[0,1]
	v_pk_add_f32 v[54:55], v[54:55], v[32:33] op_sel_hi:[1,0] neg_lo:[0,1] neg_hi:[0,1]
	v_pk_add_f32 v[72:73], v[72:73], v[32:33] op_sel_hi:[1,0] neg_lo:[0,1] neg_hi:[0,1]
	v_pk_add_f32 v[56:57], v[56:57], v[32:33] op_sel_hi:[1,0] neg_lo:[0,1] neg_hi:[0,1]
	v_pk_add_f32 v[74:75], v[74:75], v[32:33] op_sel_hi:[1,0] neg_lo:[0,1] neg_hi:[0,1]
	v_pk_add_f32 v[58:59], v[58:59], v[32:33] op_sel_hi:[1,0] neg_lo:[0,1] neg_hi:[0,1]
	v_pk_add_f32 v[76:77], v[76:77], v[32:33] op_sel_hi:[1,0] neg_lo:[0,1] neg_hi:[0,1]
	v_pk_add_f32 v[60:61], v[60:61], v[32:33] op_sel_hi:[1,0] neg_lo:[0,1] neg_hi:[0,1]
	v_pk_add_f32 v[78:79], v[78:79], v[32:33] op_sel_hi:[1,0] neg_lo:[0,1] neg_hi:[0,1]
	v_pk_add_f32 v[62:63], v[62:63], v[32:33] op_sel_hi:[1,0] neg_lo:[0,1] neg_hi:[0,1]
	v_pk_add_f32 v[32:33], v[190:191], v[34:35]
	v_pk_mul_f32 v[190:191], v[190:191], v[34:35]
	v_xor_b32_e32 v32, 0x80000000, v33
	v_mov_b32_e32 v191, v33
	v_mov_b32_e32 v33, v32
	v_mov_b32_e32 v34, v32
	v_mov_b32_e32 v35, v32
	v_mov_b32_e32 v36, v32
	v_mov_b32_e32 v37, v32
	v_mov_b32_e32 v38, v32
	v_mov_b32_e32 v39, v32
	v_mov_b32_e32 v40, v32
	v_mov_b32_e32 v41, v32
	v_mov_b32_e32 v42, v32
	v_mov_b32_e32 v43, v32
	v_mov_b32_e32 v44, v32
	v_mov_b32_e32 v45, v32
	v_mov_b32_e32 v46, v32
	v_mov_b32_e32 v47, v32
.LBB0_365:
	v_exp_f32_e32 v64, v64
	v_exp_f32_e32 v219, v48
	v_exp_f32_e32 v48, v65
	v_exp_f32_e32 v220, v49
	v_exp_f32_e32 v49, v66
	v_exp_f32_e32 v221, v50
	v_exp_f32_e32 v50, v67
	v_exp_f32_e32 v222, v51
	v_exp_f32_e32 v51, v68
	v_exp_f32_e32 v68, v52
	v_exp_f32_e32 v52, v69
	v_exp_f32_e32 v69, v53
	v_exp_f32_e32 v53, v70
	v_exp_f32_e32 v70, v54
	v_exp_f32_e32 v54, v71
	v_exp_f32_e32 v71, v55
	v_exp_f32_e32 v55, v72
	v_exp_f32_e32 v72, v56
	v_exp_f32_e32 v56, v73
	v_exp_f32_e32 v73, v57
	v_exp_f32_e32 v57, v74
	v_exp_f32_e32 v74, v58
	v_exp_f32_e32 v58, v75
	v_exp_f32_e32 v75, v59
	v_exp_f32_e32 v59, v76
	v_exp_f32_e32 v76, v60
	v_exp_f32_e32 v65, v77
	v_exp_f32_e32 v77, v61
	v_exp_f32_e32 v66, v78
	v_exp_f32_e32 v78, v62
	v_exp_f32_e32 v67, v79
	v_exp_f32_e32 v79, v63
	v_cvt_pk_bf16_f32 v224, v64, v48
	v_cvt_pk_bf16_f32 v225, v49, v50
	v_cvt_pk_bf16_f32 v226, v51, v52
	v_cvt_pk_bf16_f32 v227, v53, v54
	v_cvt_pk_bf16_f32 v228, v55, v56
	v_cvt_pk_bf16_f32 v229, v57, v58
	v_cvt_pk_bf16_f32 v230, v59, v65
	v_cvt_pk_bf16_f32 v231, v66, v67
	v_cvt_pk_bf16_f32 v232, v219, v220
	v_cvt_pk_bf16_f32 v233, v221, v222
	v_cvt_pk_bf16_f32 v234, v68, v69
	v_cvt_pk_bf16_f32 v235, v70, v71
	v_cvt_pk_bf16_f32 v236, v72, v73
	v_cvt_pk_bf16_f32 v237, v74, v75
	v_cvt_pk_bf16_f32 v238, v76, v77
	v_cvt_pk_bf16_f32 v239, v78, v79
	s_cmp_lg_u32 s98, 0
	s_cbranch_scc1 .Lstg_y_12
	s_waitcnt lgkmcnt(0)
	s_barrier
.Lstg_y_12:
	s_mul_i32 s8, s45, 0x3400
	v_add_u32_e32 v189, s8, v208
	ds_read_b128 v[60:63], v189
	ds_read_b128 v[156:159], v189 offset:32
	ds_read_b128 v[164:167], v189 offset:6656
	ds_read_b128 v[152:155], v189 offset:64
	ds_read_b128 v[160:163], v189 offset:6688
	ds_read_b128 v[148:151], v189 offset:6720
	s_waitcnt lgkmcnt(13)
	v_mfma_f32_32x32x16_bf16 v[16:31], v[140:143], v[224:227], v[16:31]
	s_mul_i32 s44, s43, 0x3400
	s_add_i32 s18, s44, 0
	s_waitcnt lgkmcnt(11)
	v_mfma_f32_32x32x16_bf16 v[0:15], v[144:147], v[224:227], v[0:15]
	v_mfma_f32_32x32x16_bf16 v[16:31], v[128:131], v[228:231], v[16:31]
	s_waitcnt lgkmcnt(10)
	v_mfma_f32_32x32x16_bf16 v[0:15], v[132:135], v[228:231], v[0:15]
	s_waitcnt lgkmcnt(9)
	v_mfma_f32_32x32x16_bf16 v[16:31], v[124:127], v[232:235], v[16:31]
	s_waitcnt lgkmcnt(7)
	v_mfma_f32_32x32x16_bf16 v[0:15], v[136:139], v[232:235], v[0:15]
	v_mfma_f32_32x32x16_bf16 v[16:31], v[120:123], v[236:239], v[16:31]
	v_add_u32_e32 v120, s18, v207
	s_waitcnt vmcnt(1)
	ds_write_b128 v120, v[112:115]
	s_waitcnt lgkmcnt(7)
	v_mfma_f32_32x32x16_bf16 v[0:15], v[116:119], v[236:239], v[0:15]
	s_and_saveexec_b64 s[8:9], s[4:5]
	v_add_u32_e32 v112, s18, v206
	ds_write_b128 v112, v[104:107]
	s_or_b64 exec, exec, s[8:9]
	v_add_f32_e32 v64, v219, v64
	v_add_f32_e32 v64, 0, v64
	v_add_f32_e32 v48, v220, v48
	v_add_f32_e32 v48, v48, v64
	v_add_f32_e32 v49, v221, v49
	v_add_f32_e32 v48, v49, v48
	v_add_f32_e32 v49, v222, v50
	v_add_f32_e32 v48, v49, v48
	v_add_f32_e32 v49, v68, v51
	v_add_f32_e32 v48, v49, v48
	v_add_f32_e32 v49, v69, v52
	v_add_f32_e32 v48, v49, v48
	v_add_f32_e32 v49, v70, v53
	v_add_f32_e32 v48, v49, v48
	v_add_f32_e32 v49, v71, v54
	v_add_f32_e32 v48, v49, v48
	v_add_f32_e32 v49, v72, v55
	v_add_f32_e32 v48, v49, v48
	v_add_f32_e32 v49, v73, v56
	v_add_f32_e32 v48, v49, v48
	v_add_f32_e32 v49, v74, v57
	v_add_f32_e32 v48, v49, v48
	v_add_f32_e32 v49, v75, v58
	v_add_f32_e32 v48, v49, v48
	v_add_f32_e32 v49, v76, v59
	v_add_f32_e32 v48, v49, v48
	v_add_f32_e32 v49, v77, v65
	v_add_f32_e32 v48, v49, v48
	v_add_f32_e32 v49, v78, v66
	v_add_f32_e32 v48, v49, v48
	v_add_f32_e32 v49, v79, v67
	s_cmp_eq_u32 s72, 1
	v_add_f32_e32 v48, v49, v48
	s_cselect_b32 s8, 0, 0x2400
	v_add_f32_e32 v190, v190, v48
	v_add_u32_e32 v48, s8, v198
	v_add_u32_e32 v48, 0x9800, v48
	s_waitcnt vmcnt(0)
	ds_write2_b64 v48, v[108:109], v[110:111] offset0:128 offset1:130
	s_add_i32 s33, s33, 1
	v_lshl_add_u64 v[194:195], v[194:195], 0, s[36:37]
	s_cmp_eq_u32 s33, 31
	v_lshl_add_u64 v[196:197], v[196:197], 0, s[22:23]
	s_cbranch_scc1 .LBB0_369
	s_mov_b32 s8, s42
	s_mov_b32 s42, s45
	s_branch .LBB0_361
.LBB0_369:
	s_waitcnt lgkmcnt(7)
	v_mfma_f32_32x32x16_bf16 v[64:79], v[60:63], v[80:83], v[32:47]
	ds_read_b128 v[104:107], v189 offset:96
	ds_read_b128 v[108:111], v189 offset:128
	s_waitcnt lgkmcnt(7)
	v_mfma_f32_32x32x16_bf16 v[48:63], v[164:167], v[80:83], v[32:47]
	v_mfma_f32_32x32x16_bf16 v[64:79], v[156:159], v[84:87], v[64:79]
	s_waitcnt lgkmcnt(5)
	v_mfma_f32_32x32x16_bf16 v[48:63], v[160:163], v[84:87], v[48:63]
	v_mfma_f32_32x32x16_bf16 v[64:79], v[152:155], v[88:91], v[64:79]
	s_waitcnt lgkmcnt(4)
	v_mfma_f32_32x32x16_bf16 v[48:63], v[148:151], v[88:91], v[48:63]
	s_waitcnt lgkmcnt(1)
	v_mfma_f32_32x32x16_bf16 v[64:79], v[104:107], v[92:95], v[64:79]
	ds_read_b128 v[104:107], v189 offset:6752
	ds_read_b128 v[112:115], v189 offset:160
	s_waitcnt lgkmcnt(1)
	v_mfma_f32_32x32x16_bf16 v[48:63], v[104:107], v[92:95], v[48:63]
	v_mfma_f32_32x32x16_bf16 v[64:79], v[108:111], v[96:99], v[64:79]
	ds_read_b128 v[104:107], v189 offset:6784
	ds_read_b128 v[108:111], v189 offset:6816
	s_waitcnt lgkmcnt(1)
	v_mfma_f32_32x32x16_bf16 v[48:63], v[104:107], v[96:99], v[48:63]
	v_mfma_f32_32x32x16_bf16 v[64:79], v[112:115], v[100:103], v[64:79]
	s_waitcnt lgkmcnt(0)
	v_mfma_f32_32x32x16_bf16 v[48:63], v[108:111], v[100:103], v[48:63]
	ds_read_b128 v[132:135], v209 offset:39936
	ds_read_b128 v[120:123], v209 offset:39968
	ds_read_b128 v[136:139], v209 offset:44544
	ds_read_b128 v[124:127], v209 offset:44576
	ds_read_b128 v[116:119], v209 offset:40000
	ds_read_b128 v[108:111], v209 offset:40032
	ds_read_b128 v[128:131], v209 offset:44608
	ds_read_b128 v[112:115], v209 offset:44640
	s_nop 1
	v_max3_f32 v140, v64, v65, v66
	s_nop 0
	v_max3_f32 v141, v48, v49, v50
	v_max3_f32 v140, v140, v67, v68
	v_max3_f32 v141, v141, v51, v52
	v_max3_f32 v140, v140, v69, v70
	v_max3_f32 v141, v141, v53, v54
	v_max3_f32 v140, v140, v71, v72
	v_max3_f32 v141, v141, v55, v56
	v_max3_f32 v140, v140, v73, v74
	v_max3_f32 v141, v141, v57, v58
	v_max3_f32 v140, v140, v75, v76
	v_max3_f32 v141, v141, v59, v60
	v_max_f32_e32 v142, v63, v63
	v_max_f32_e32 v143, v79, v79
	v_max3_f32 v140, v140, v77, v78
	v_max3_f32 v141, v141, v61, v62
	v_max_f32_e32 v142, v143, v142
	v_max3_f32 v140, v140, v141, v142
	v_mov_b32_e32 v141, v140
	s_nop 1
	v_permlane32_swap_b32_e32 v140, v141
	v_max_f32_e32 v141, v141, v141
	v_max_f32_e32 v140, v140, v140
	v_max_f32_e32 v140, v140, v141
	s_cmp_eq_u32 s98, 0
	s_cbranch_scc1 .Lstg_x_13
	s_waitcnt lgkmcnt(0)
	s_barrier
.Lstg_x_13:
	v_cmp_lt_f32_e32 vcc, s68, v140
	s_cbranch_vccz .LBB0_371
	v_max_f32_e32 v32, v140, v140
	v_max_f32_e32 v34, 0, v32
	v_exp_f32_e64 v36, -v34
	v_add_f32_e32 v191, v191, v34
	v_xor_b32_e32 v32, 0x80000000, v191
	v_pk_add_f32 v[64:65], v[64:65], v[34:35] op_sel_hi:[1,0] neg_lo:[0,1] neg_hi:[0,1]
	v_pk_mul_f32 v[14:15], v[14:15], v[36:37] op_sel_hi:[1,0]
	v_pk_mul_f32 v[12:13], v[12:13], v[36:37] op_sel_hi:[1,0]
	v_pk_mul_f32 v[10:11], v[10:11], v[36:37] op_sel_hi:[1,0]
	v_pk_mul_f32 v[8:9], v[8:9], v[36:37] op_sel_hi:[1,0]
	v_pk_mul_f32 v[6:7], v[6:7], v[36:37] op_sel_hi:[1,0]
	v_pk_mul_f32 v[4:5], v[4:5], v[36:37] op_sel_hi:[1,0]
	v_pk_mul_f32 v[2:3], v[2:3], v[36:37] op_sel_hi:[1,0]
	v_pk_mul_f32 v[0:1], v[0:1], v[36:37] op_sel_hi:[1,0]
	v_pk_add_f32 v[48:49], v[48:49], v[34:35] op_sel_hi:[1,0] neg_lo:[0,1] neg_hi:[0,1]
	v_pk_add_f32 v[66:67], v[66:67], v[34:35] op_sel_hi:[1,0] neg_lo:[0,1] neg_hi:[0,1]
	v_pk_add_f32 v[50:51], v[50:51], v[34:35] op_sel_hi:[1,0] neg_lo:[0,1] neg_hi:[0,1]
	v_pk_add_f32 v[68:69], v[68:69], v[34:35] op_sel_hi:[1,0] neg_lo:[0,1] neg_hi:[0,1]
	v_pk_add_f32 v[52:53], v[52:53], v[34:35] op_sel_hi:[1,0] neg_lo:[0,1] neg_hi:[0,1]
	v_pk_add_f32 v[70:71], v[70:71], v[34:35] op_sel_hi:[1,0] neg_lo:[0,1] neg_hi:[0,1]
	v_pk_add_f32 v[54:55], v[54:55], v[34:35] op_sel_hi:[1,0] neg_lo:[0,1] neg_hi:[0,1]
	v_pk_add_f32 v[72:73], v[72:73], v[34:35] op_sel_hi:[1,0] neg_lo:[0,1] neg_hi:[0,1]
	v_pk_add_f32 v[56:57], v[56:57], v[34:35] op_sel_hi:[1,0] neg_lo:[0,1] neg_hi:[0,1]
	v_pk_add_f32 v[74:75], v[74:75], v[34:35] op_sel_hi:[1,0] neg_lo:[0,1] neg_hi:[0,1]
	v_pk_add_f32 v[58:59], v[58:59], v[34:35] op_sel_hi:[1,0] neg_lo:[0,1] neg_hi:[0,1]
	v_pk_add_f32 v[76:77], v[76:77], v[34:35] op_sel_hi:[1,0] neg_lo:[0,1] neg_hi:[0,1]
	v_pk_add_f32 v[60:61], v[60:61], v[34:35] op_sel_hi:[1,0] neg_lo:[0,1] neg_hi:[0,1]
	v_pk_add_f32 v[78:79], v[78:79], v[34:35] op_sel_hi:[1,0] neg_lo:[0,1] neg_hi:[0,1]
	v_pk_add_f32 v[62:63], v[62:63], v[34:35] op_sel_hi:[1,0] neg_lo:[0,1] neg_hi:[0,1]
	v_pk_mul_f32 v[30:31], v[30:31], v[36:37] op_sel_hi:[1,0]
	v_pk_mul_f32 v[28:29], v[28:29], v[36:37] op_sel_hi:[1,0]
	v_pk_mul_f32 v[26:27], v[26:27], v[36:37] op_sel_hi:[1,0]
	v_pk_mul_f32 v[24:25], v[24:25], v[36:37] op_sel_hi:[1,0]
	v_pk_mul_f32 v[22:23], v[22:23], v[36:37] op_sel_hi:[1,0]
	v_pk_mul_f32 v[20:21], v[20:21], v[36:37] op_sel_hi:[1,0]
	v_pk_mul_f32 v[18:19], v[18:19], v[36:37] op_sel_hi:[1,0]
	v_pk_mul_f32 v[16:17], v[16:17], v[36:37] op_sel_hi:[1,0]
	v_mul_f32_e32 v190, v190, v36
	v_mov_b32_e32 v33, v32
	v_mov_b32_e32 v34, v32
	v_mov_b32_e32 v35, v32
	v_mov_b32_e32 v36, v32
	v_mov_b32_e32 v37, v32
	v_mov_b32_e32 v38, v32
	v_mov_b32_e32 v39, v32
	v_mov_b32_e32 v40, v32
	v_mov_b32_e32 v41, v32
	v_mov_b32_e32 v42, v32
	v_mov_b32_e32 v43, v32
	v_mov_b32_e32 v44, v32
	v_mov_b32_e32 v45, v32
	v_mov_b32_e32 v46, v32
	v_mov_b32_e32 v47, v32
.LBB0_371:
	v_exp_f32_e32 v141, v64
	v_exp_f32_e32 v142, v48
	v_exp_f32_e32 v143, v65
	v_exp_f32_e32 v144, v49
	v_exp_f32_e32 v145, v66
	v_add_f32_e32 v48, v142, v141
	v_exp_f32_e32 v146, v50
	v_add_f32_e32 v48, 0, v48
	v_add_f32_e32 v49, v144, v143
	v_exp_f32_e32 v147, v67
	v_exp_f32_e32 v148, v51
	v_add_f32_e32 v64, v49, v48
	v_exp_f32_e32 v49, v68
	v_exp_f32_e32 v51, v52
	v_exp_f32_e32 v48, v69
	v_exp_f32_e32 v50, v53
	v_add_f32_e32 v65, v146, v145
	v_add_f32_e32 v52, v65, v64
	v_add_f32_e32 v53, v148, v147
	v_add_f32_e32 v64, v53, v52
	v_pk_add_f32 v[52:53], v[50:51], v[48:49]
	v_exp_f32_e32 v65, v70
	v_add_f32_e32 v53, v53, v64
	v_exp_f32_e32 v67, v54
	v_exp_f32_e32 v64, v71
	v_exp_f32_e32 v66, v55
	v_pk_mov_b32 v[54:55], v[48:49], v[48:49] op_sel:[1,0]
	v_pk_mov_b32 v[68:69], v[50:51], v[50:51] op_sel:[1,0]
	v_add_f32_e32 v50, v52, v53
	v_pk_add_f32 v[48:49], v[66:67], v[64:65]
	v_exp_f32_e32 v51, v72
	v_add_f32_e32 v49, v49, v50
	v_exp_f32_e32 v53, v56
	v_exp_f32_e32 v50, v73
	v_exp_f32_e32 v52, v57
	v_pk_mov_b32 v[56:57], v[64:65], v[64:65] op_sel:[1,0]
	v_pk_mov_b32 v[64:65], v[66:67], v[66:67] op_sel:[1,0]
	v_add_f32_e32 v66, v48, v49
	v_pk_add_f32 v[48:49], v[52:53], v[50:51]
	v_exp_f32_e32 v67, v74
	v_add_f32_e32 v49, v49, v66
	v_exp_f32_e32 v71, v58
	v_exp_f32_e32 v66, v75
	v_exp_f32_e32 v70, v59
	v_pk_mov_b32 v[58:59], v[50:51], v[50:51] op_sel:[1,0]
	v_add_f32_e32 v50, v48, v49
	v_pk_mov_b32 v[72:73], v[52:53], v[52:53] op_sel:[1,0]
	v_pk_add_f32 v[48:49], v[70:71], v[66:67]
	v_exp_f32_e32 v51, v76
	v_add_f32_e32 v49, v49, v50
	v_exp_f32_e32 v53, v60
	v_exp_f32_e32 v50, v77
	v_exp_f32_e32 v52, v61
	v_pk_mov_b32 v[60:61], v[66:67], v[66:67] op_sel:[1,0]
	v_pk_mov_b32 v[66:67], v[70:71], v[70:71] op_sel:[1,0]
	v_add_f32_e32 v70, v48, v49
	v_pk_add_f32 v[48:49], v[52:53], v[50:51]
	v_exp_f32_e32 v71, v78
	v_add_f32_e32 v49, v49, v70
	v_exp_f32_e32 v75, v62
	v_exp_f32_e32 v70, v79
	v_exp_f32_e32 v74, v63
	v_pk_mov_b32 v[62:63], v[50:51], v[50:51] op_sel:[1,0]
	v_add_f32_e32 v50, v48, v49
	v_pk_mov_b32 v[76:77], v[52:53], v[52:53] op_sel:[1,0]
	v_pk_add_f32 v[48:49], v[74:75], v[70:71]
	v_pk_mov_b32 v[70:71], v[70:71], v[70:71] op_sel:[1,0]
	v_add_f32_e32 v49, v49, v50
	v_pk_mov_b32 v[74:75], v[74:75], v[74:75] op_sel:[1,0]
	v_add_f32_e32 v48, v48, v49
	v_add_f32_e32 v140, v190, v48
	v_cvt_pk_bf16_f32 v48, v141, v143
	v_cvt_pk_bf16_f32 v49, v145, v147
	v_cvt_pk_bf16_f32 v50, v54, v55
	v_cvt_pk_bf16_f32 v51, v56, v57
	v_cvt_pk_bf16_f32 v52, v58, v59
	v_cvt_pk_bf16_f32 v53, v60, v61
	v_cvt_pk_bf16_f32 v54, v62, v63
	v_cvt_pk_bf16_f32 v55, v70, v71
	v_cvt_pk_bf16_f32 v56, v142, v144
	v_cvt_pk_bf16_f32 v57, v146, v148
	v_cvt_pk_bf16_f32 v58, v68, v69
	v_cvt_pk_bf16_f32 v59, v64, v65
	v_cvt_pk_bf16_f32 v60, v72, v73
	v_cvt_pk_bf16_f32 v61, v66, v67
	v_cvt_pk_bf16_f32 v62, v76, v77
	v_cvt_pk_bf16_f32 v63, v74, v75
	s_cmp_lg_u32 s98, 0
	s_cbranch_scc1 .Lstg_y_14
	s_waitcnt lgkmcnt(0)
	s_barrier
.Lstg_y_14:
	v_add_u32_e32 v141, s44, v208
	ds_read_b128 v[64:67], v141
	ds_read_b128 v[68:71], v141 offset:32
	ds_read_b128 v[72:75], v141 offset:6656
	ds_read_b128 v[76:79], v141 offset:64
	ds_read_b128 v[142:145], v141 offset:6688
	ds_read_b128 v[146:149], v141 offset:6720
	s_waitcnt lgkmcnt(13)
	v_mfma_f32_32x32x16_bf16 v[16:31], v[132:135], v[48:51], v[16:31]
	s_waitcnt lgkmcnt(12)
	v_mfma_f32_32x32x16_bf16 v[0:15], v[136:139], v[48:51], v[0:15]
	v_mfma_f32_32x32x16_bf16 v[16:31], v[120:123], v[52:55], v[16:31]
	s_waitcnt lgkmcnt(11)
	v_mfma_f32_32x32x16_bf16 v[0:15], v[124:127], v[52:55], v[0:15]
	s_waitcnt lgkmcnt(10)
	v_mfma_f32_32x32x16_bf16 v[16:31], v[116:119], v[56:59], v[16:31]
	s_waitcnt lgkmcnt(8)
	v_mfma_f32_32x32x16_bf16 v[0:15], v[128:131], v[56:59], v[0:15]
	v_mfma_f32_32x32x16_bf16 v[16:31], v[108:111], v[60:63], v[16:31]
	s_waitcnt lgkmcnt(7)
	v_mfma_f32_32x32x16_bf16 v[0:15], v[112:115], v[60:63], v[0:15]
	s_waitcnt lgkmcnt(6)
	v_mfma_f32_32x32x16_bf16 v[48:63], v[64:67], v[80:83], v[32:47]
	s_waitcnt lgkmcnt(4)
	v_mfma_f32_32x32x16_bf16 v[32:47], v[72:75], v[80:83], v[32:47]
	v_mfma_f32_32x32x16_bf16 v[48:63], v[68:71], v[84:87], v[48:63]
	ds_read_b128 v[64:67], v141 offset:96
	ds_read_b128 v[68:71], v141 offset:128
	s_waitcnt lgkmcnt(4)
	v_mfma_f32_32x32x16_bf16 v[32:47], v[142:145], v[84:87], v[32:47]
	v_mfma_f32_32x32x16_bf16 v[48:63], v[76:79], v[88:91], v[48:63]
	s_waitcnt lgkmcnt(3)
	v_mfma_f32_32x32x16_bf16 v[32:47], v[146:149], v[88:91], v[32:47]
	s_waitcnt lgkmcnt(1)
	v_mfma_f32_32x32x16_bf16 v[48:63], v[64:67], v[92:95], v[48:63]
	ds_read_b128 v[64:67], v141 offset:6752
	ds_read_b128 v[72:75], v141 offset:160
	s_waitcnt lgkmcnt(1)
	v_mfma_f32_32x32x16_bf16 v[32:47], v[64:67], v[92:95], v[32:47]
	v_mfma_f32_32x32x16_bf16 v[48:63], v[68:71], v[96:99], v[48:63]
	ds_read_b128 v[64:67], v141 offset:6784
	ds_read_b128 v[68:71], v141 offset:6816
	s_waitcnt lgkmcnt(1)
	v_mfma_f32_32x32x16_bf16 v[32:47], v[64:67], v[96:99], v[32:47]
	v_mfma_f32_32x32x16_bf16 v[48:63], v[72:75], v[100:103], v[48:63]
	s_waitcnt lgkmcnt(0)
	v_mfma_f32_32x32x16_bf16 v[32:47], v[68:71], v[100:103], v[32:47]
	ds_read_b128 v[104:107], v209 offset:49152
	ds_read_b128 v[96:99], v209 offset:49184
	ds_read_b128 v[108:111], v209 offset:53760
	ds_read_b128 v[100:103], v209 offset:53792
	ds_read_b128 v[92:95], v209 offset:49216
	ds_read_b128 v[84:87], v209 offset:49248
	ds_read_b128 v[88:91], v209 offset:53824
	ds_read_b128 v[80:83], v209 offset:53856
	s_nop 1
	v_max3_f32 v64, v48, v49, v50
	s_nop 0
	v_max3_f32 v65, v32, v33, v34
	v_max3_f32 v64, v64, v51, v52
	v_max3_f32 v65, v65, v35, v36
	v_max3_f32 v64, v64, v53, v54
	v_max3_f32 v65, v65, v37, v38
	v_max3_f32 v64, v64, v55, v56
	v_max3_f32 v65, v65, v39, v40
	v_max3_f32 v64, v64, v57, v58
	v_max3_f32 v65, v65, v41, v42
	v_max3_f32 v64, v64, v59, v60
	v_max3_f32 v65, v65, v43, v44
	v_max_f32_e32 v66, v47, v47
	v_max_f32_e32 v67, v63, v63
	v_max3_f32 v64, v64, v61, v62
	v_max3_f32 v65, v65, v45, v46
	v_max_f32_e32 v66, v67, v66
	v_max3_f32 v64, v64, v65, v66
	v_mov_b32_e32 v65, v64
	s_nop 1
	v_permlane32_swap_b32_e32 v64, v65
	v_max_f32_e32 v65, v65, v65
	v_max_f32_e32 v64, v64, v64
	v_max_f32_e32 v64, v64, v65
	s_cmp_eq_u32 s98, 0
	s_cbranch_scc1 .Lstg_x_15
	s_waitcnt lgkmcnt(0)
	s_barrier
.Lstg_x_15:
	v_cmp_lt_f32_e32 vcc, s68, v64
	s_cbranch_vccz .LBB0_373
	v_max_f32_e32 v64, v64, v64
	v_max_f32_e32 v66, 0, v64
	v_exp_f32_e64 v68, -v66
	v_add_f32_e32 v64, v191, v66
	v_xor_b32_e32 v64, 0x80000000, v64
	v_pk_add_f32 v[48:49], v[48:49], v[66:67] op_sel_hi:[1,0] neg_lo:[0,1] neg_hi:[0,1]
	v_pk_mul_f32 v[14:15], v[14:15], v[68:69] op_sel_hi:[1,0]
	v_pk_mul_f32 v[12:13], v[12:13], v[68:69] op_sel_hi:[1,0]
	v_pk_mul_f32 v[10:11], v[10:11], v[68:69] op_sel_hi:[1,0]
	v_pk_mul_f32 v[8:9], v[8:9], v[68:69] op_sel_hi:[1,0]
	v_pk_mul_f32 v[6:7], v[6:7], v[68:69] op_sel_hi:[1,0]
	v_pk_mul_f32 v[4:5], v[4:5], v[68:69] op_sel_hi:[1,0]
	v_pk_mul_f32 v[2:3], v[2:3], v[68:69] op_sel_hi:[1,0]
	v_pk_mul_f32 v[0:1], v[0:1], v[68:69] op_sel_hi:[1,0]
	v_pk_add_f32 v[32:33], v[32:33], v[66:67] op_sel_hi:[1,0] neg_lo:[0,1] neg_hi:[0,1]
	v_pk_add_f32 v[50:51], v[50:51], v[66:67] op_sel_hi:[1,0] neg_lo:[0,1] neg_hi:[0,1]
	v_pk_add_f32 v[34:35], v[34:35], v[66:67] op_sel_hi:[1,0] neg_lo:[0,1] neg_hi:[0,1]
	v_pk_add_f32 v[52:53], v[52:53], v[66:67] op_sel_hi:[1,0] neg_lo:[0,1] neg_hi:[0,1]
	v_pk_add_f32 v[36:37], v[36:37], v[66:67] op_sel_hi:[1,0] neg_lo:[0,1] neg_hi:[0,1]
	v_pk_add_f32 v[54:55], v[54:55], v[66:67] op_sel_hi:[1,0] neg_lo:[0,1] neg_hi:[0,1]
	v_pk_add_f32 v[38:39], v[38:39], v[66:67] op_sel_hi:[1,0] neg_lo:[0,1] neg_hi:[0,1]
	v_pk_add_f32 v[56:57], v[56:57], v[66:67] op_sel_hi:[1,0] neg_lo:[0,1] neg_hi:[0,1]
	v_pk_add_f32 v[40:41], v[40:41], v[66:67] op_sel_hi:[1,0] neg_lo:[0,1] neg_hi:[0,1]
	v_pk_add_f32 v[58:59], v[58:59], v[66:67] op_sel_hi:[1,0] neg_lo:[0,1] neg_hi:[0,1]
	v_pk_add_f32 v[42:43], v[42:43], v[66:67] op_sel_hi:[1,0] neg_lo:[0,1] neg_hi:[0,1]
	v_pk_add_f32 v[60:61], v[60:61], v[66:67] op_sel_hi:[1,0] neg_lo:[0,1] neg_hi:[0,1]
	v_pk_add_f32 v[44:45], v[44:45], v[66:67] op_sel_hi:[1,0] neg_lo:[0,1] neg_hi:[0,1]
	v_pk_add_f32 v[62:63], v[62:63], v[66:67] op_sel_hi:[1,0] neg_lo:[0,1] neg_hi:[0,1]
	v_pk_add_f32 v[46:47], v[46:47], v[66:67] op_sel_hi:[1,0] neg_lo:[0,1] neg_hi:[0,1]
	v_pk_mul_f32 v[30:31], v[30:31], v[68:69] op_sel_hi:[1,0]
	v_pk_mul_f32 v[28:29], v[28:29], v[68:69] op_sel_hi:[1,0]
	v_pk_mul_f32 v[26:27], v[26:27], v[68:69] op_sel_hi:[1,0]
	v_pk_mul_f32 v[24:25], v[24:25], v[68:69] op_sel_hi:[1,0]
	v_pk_mul_f32 v[22:23], v[22:23], v[68:69] op_sel_hi:[1,0]
	v_pk_mul_f32 v[20:21], v[20:21], v[68:69] op_sel_hi:[1,0]
	v_pk_mul_f32 v[18:19], v[18:19], v[68:69] op_sel_hi:[1,0]
	v_pk_mul_f32 v[16:17], v[16:17], v[68:69] op_sel_hi:[1,0]
	v_mul_f32_e32 v140, v140, v68
	v_mov_b32_e32 v65, v64
	v_mov_b32_e32 v66, v64
	v_mov_b32_e32 v67, v64
	v_mov_b32_e32 v68, v64
	v_mov_b32_e32 v69, v64
	v_mov_b32_e32 v70, v64
	v_mov_b32_e32 v71, v64
	v_mov_b32_e32 v72, v64
	v_mov_b32_e32 v73, v64
	v_mov_b32_e32 v74, v64
	v_mov_b32_e32 v75, v64
	v_mov_b32_e32 v76, v64
	v_mov_b32_e32 v77, v64
	v_mov_b32_e32 v78, v64
	v_mov_b32_e32 v79, v64
.LBB0_373:
	s_nop 0
	v_exp_f32_e32 v64, v48
	v_exp_f32_e32 v65, v32
	v_exp_f32_e32 v66, v49
	v_exp_f32_e32 v67, v33
	v_exp_f32_e32 v68, v50
	v_exp_f32_e32 v69, v34
	v_exp_f32_e32 v70, v51
	v_exp_f32_e32 v71, v35
	v_add_f32_e32 v32, v65, v64
	v_exp_f32_e32 v72, v52
	v_exp_f32_e32 v73, v36
	v_add_f32_e32 v32, 0, v32
	v_add_f32_e32 v33, v67, v66
	v_exp_f32_e32 v74, v53
	v_exp_f32_e32 v75, v37
	v_add_f32_e32 v32, v33, v32
	v_add_f32_e32 v33, v69, v68
	v_exp_f32_e32 v54, v54
	v_exp_f32_e32 v76, v38
	v_add_f32_e32 v32, v33, v32
	v_add_f32_e32 v33, v71, v70
	v_exp_f32_e32 v55, v55
	v_exp_f32_e32 v77, v39
	v_add_f32_e32 v32, v33, v32
	v_add_f32_e32 v33, v73, v72
	v_add_f32_e32 v32, v33, v32
	v_add_f32_e32 v33, v75, v74
	v_add_f32_e32 v32, v33, v32
	v_add_f32_e32 v33, v76, v54
	v_add_f32_e32 v32, v33, v32
	v_add_f32_e32 v33, v77, v55
	v_add_f32_e32 v50, v33, v32
	v_exp_f32_e32 v33, v56
	v_exp_f32_e32 v35, v40
	v_exp_f32_e32 v32, v57
	v_exp_f32_e32 v34, v41
	v_exp_f32_e32 v49, v58
	v_exp_f32_e32 v37, v42
	v_exp_f32_e32 v48, v59
	v_exp_f32_e32 v36, v43
	v_pk_add_f32 v[38:39], v[34:35], v[32:33]
	v_exp_f32_e32 v51, v60
	v_add_f32_e32 v39, v39, v50
	v_add_f32_e32 v40, v38, v39
	v_pk_add_f32 v[38:39], v[36:37], v[48:49]
	v_exp_f32_e32 v50, v61
	v_add_f32_e32 v39, v39, v40
	v_add_f32_e32 v56, v38, v39
	v_exp_f32_e32 v39, v44
	v_exp_f32_e32 v38, v45
	v_exp_f32_e32 v53, v62
	v_exp_f32_e32 v41, v46
	v_exp_f32_e32 v52, v63
	v_exp_f32_e32 v40, v47
	v_pk_add_f32 v[42:43], v[38:39], v[50:51]
	s_nop 0
	v_add_f32_e32 v43, v43, v56
	v_add_f32_e32 v44, v42, v43
	v_pk_add_f32 v[42:43], v[40:41], v[52:53]
	s_nop 0
	v_add_f32_e32 v43, v43, v44
	v_add_f32_e32 v42, v42, v43
	v_add_f32_e32 v56, v140, v42
	v_pk_mov_b32 v[32:33], v[32:33], v[32:33] op_sel:[1,0]
	v_pk_mov_b32 v[34:35], v[34:35], v[34:35] op_sel:[1,0]
	v_pk_mov_b32 v[36:37], v[36:37], v[36:37] op_sel:[1,0]
	v_cvt_pk_bf16_f32 v42, v32, v33
	v_pk_mov_b32 v[32:33], v[48:49], v[48:49] op_sel:[1,0]
	v_cvt_pk_bf16_f32 v34, v34, v35
	v_cvt_pk_bf16_f32 v35, v36, v37
	v_pk_mov_b32 v[36:37], v[38:39], v[38:39] op_sel:[1,0]
	v_pk_mov_b32 v[38:39], v[40:41], v[40:41] op_sel:[1,0]
	v_cvt_pk_bf16_f32 v43, v32, v33
	v_pk_mov_b32 v[32:33], v[50:51], v[50:51] op_sel:[1,0]
	v_cvt_pk_bf16_f32 v36, v36, v37
	v_cvt_pk_bf16_f32 v37, v38, v39
	v_cvt_pk_bf16_f32 v38, v65, v67
	v_cvt_pk_bf16_f32 v39, v69, v71
	v_cvt_pk_bf16_f32 v44, v32, v33
	v_pk_mov_b32 v[32:33], v[52:53], v[52:53] op_sel:[1,0]
	v_cvt_pk_bf16_f32 v40, v73, v75
	v_cvt_pk_bf16_f32 v41, v76, v77
	v_cvt_pk_bf16_f32 v45, v32, v33
	v_cvt_pk_bf16_f32 v46, v64, v66
	v_cvt_pk_bf16_f32 v47, v68, v70
	v_cvt_pk_bf16_f32 v48, v72, v74
	v_cvt_pk_bf16_f32 v49, v54, v55
	s_cmp_lg_u32 s98, 0
	s_cbranch_scc1 .Lstg_y_16
	s_waitcnt lgkmcnt(0)
	s_barrier
.Lstg_y_16:
	s_waitcnt lgkmcnt(5)
	s_nop 0
	v_mfma_f32_32x32x16_bf16 v[0:15], v[108:111], v[46:49], v[0:15]
	ds_bpermute_b32 v32, v218, v56
	s_waitcnt lgkmcnt(0)
	v_add_f32_e32 v32, v56, v32
	v_div_scale_f32 v33, s[8:9], v32, v32, 1.0
	v_mfma_f32_32x32x16_bf16 v[16:31], v[104:107], v[46:49], v[16:31]
	v_mfma_f32_32x32x16_bf16 v[0:15], v[100:103], v[42:45], v[0:15]
	v_mfma_f32_32x32x16_bf16 v[16:31], v[96:99], v[42:45], v[16:31]
	v_rcp_f32_e32 v42, v33
	v_mfma_f32_32x32x16_bf16 v[0:15], v[88:91], v[38:41], v[0:15]
	v_mfma_f32_32x32x16_bf16 v[16:31], v[92:95], v[38:41], v[16:31]
	v_fma_f32 v38, -v33, v42, 1.0
	v_fmac_f32_e32 v42, v38, v42
	v_div_scale_f32 v38, vcc, 1.0, v32, 1.0
	v_mul_f32_e32 v39, v38, v42
	v_fma_f32 v40, -v33, v39, v38
	v_fmac_f32_e32 v39, v40, v42
	v_mfma_f32_32x32x16_bf16 v[0:15], v[80:83], v[34:37], v[0:15]
	v_fma_f32 v33, -v33, v39, v38
	v_div_fmas_f32 v33, v33, v42, v39
	v_div_fixup_f32 v40, v33, v32, 1.0
	v_mfma_f32_32x32x16_bf16 v[16:31], v[84:87], v[34:37], v[16:31]
	s_nop 7
	v_mul_f32_e64 v0, v0, v40
	v_mul_f32_e64 v1, v1, v40
	v_mul_f32_e64 v2, v2, v40
	v_mul_f32_e64 v3, v3, v40
	v_pk_mul_f32 v[32:33], v[16:17], v[40:41] op_sel_hi:[1,0]
	v_pk_mul_f32 v[16:17], v[0:1], v[0:1]
	v_pk_mul_f32 v[34:35], v[18:19], v[40:41] op_sel_hi:[1,0]
	v_pk_fma_f32 v[42:43], v[32:33], v[32:33], v[16:17]
	v_pk_mul_f32 v[16:17], v[2:3], v[2:3]
	v_pk_mul_f32 v[36:37], v[20:21], v[40:41] op_sel_hi:[1,0]
	v_pk_fma_f32 v[44:45], v[34:35], v[34:35], v[16:17]
	v_pk_mul_f32 v[16:17], v[4:5], v[40:41] op_sel_hi:[1,0]
	v_pk_mul_f32 v[18:19], v[6:7], v[40:41] op_sel_hi:[1,0]
	v_pk_mul_f32 v[4:5], v[16:17], v[16:17]
	v_pk_mul_f32 v[38:39], v[22:23], v[40:41] op_sel_hi:[1,0]
	v_pk_fma_f32 v[46:47], v[36:37], v[36:37], v[4:5]
	v_pk_mul_f32 v[4:5], v[18:19], v[18:19]
	v_pk_mul_f32 v[20:21], v[24:25], v[40:41] op_sel_hi:[1,0]
	v_pk_fma_f32 v[48:49], v[38:39], v[38:39], v[4:5]
	v_pk_mul_f32 v[4:5], v[8:9], v[40:41] op_sel_hi:[1,0]
	v_pk_mul_f32 v[22:23], v[26:27], v[40:41] op_sel_hi:[1,0]
	v_pk_mul_f32 v[6:7], v[4:5], v[4:5]
	v_pk_mul_f32 v[24:25], v[28:29], v[40:41] op_sel_hi:[1,0]
	v_pk_fma_f32 v[50:51], v[20:21], v[20:21], v[6:7]
	v_pk_mul_f32 v[6:7], v[10:11], v[40:41] op_sel_hi:[1,0]
	s_nop 0
	v_pk_mul_f32 v[8:9], v[6:7], v[6:7]
	s_nop 0
	v_pk_fma_f32 v[26:27], v[22:23], v[22:23], v[8:9]
	v_pk_mul_f32 v[8:9], v[12:13], v[40:41] op_sel_hi:[1,0]
	v_pk_mul_f32 v[12:13], v[30:31], v[40:41] op_sel_hi:[1,0]
	v_add_f32_e32 v30, v42, v43
	v_add_f32_e32 v30, v44, v30
	v_add_f32_e32 v30, v45, v30
	v_add_f32_e32 v30, v46, v30
	v_add_f32_e32 v30, v47, v30
	v_add_f32_e32 v30, v48, v30
	v_add_f32_e32 v30, v49, v30
	v_add_f32_e32 v30, v50, v30
	v_add_f32_e32 v30, v51, v30
	v_pk_mul_f32 v[10:11], v[8:9], v[8:9]
	v_add_f32_e32 v26, v26, v30
	v_pk_fma_f32 v[28:29], v[24:25], v[24:25], v[10:11]
	v_pk_mul_f32 v[10:11], v[14:15], v[40:41] op_sel_hi:[1,0]
	v_add_f32_e32 v26, v27, v26
	v_pk_mul_f32 v[14:15], v[10:11], v[10:11]
	v_add_f32_e32 v26, v28, v26
	v_pk_fma_f32 v[14:15], v[12:13], v[12:13], v[14:15]
	v_add_f32_e32 v26, v29, v26
	v_add_f32_e32 v14, v14, v26
	v_add_f32_e32 v14, v15, v14
	ds_bpermute_b32 v15, v218, v14
	s_and_saveexec_b64 s[8:9], s[6:7]
	s_cbranch_execz .LBB0_332
	s_lshl_b32 s1, s1, 2
	v_readlane_b32 s18, v242, 33
	s_add_u32 s1, s18, s1
	v_readlane_b32 s18, v242, 34
	s_addc_u32 s18, s18, 0
	s_lshl_b32 s0, s0, 2
	s_add_u32 s19, s1, s0
	s_addc_u32 s18, s18, 0
	s_lshl_b64 s[0:1], s[14:15], 2
	s_add_u32 s0, s19, s0
	s_addc_u32 s1, s18, s1
	v_lshlrev_b32_e32 v26, 2, v170
	s_waitcnt lgkmcnt(0)
	v_add_f32_e32 v14, v14, v15
	global_atomic_add_f32 v26, v14, s[0:1]
	s_branch .LBB0_332

	.amdhsa_kernel _Z10fwd_kernel4Args
		.amdhsa_group_segment_fixed_size 0
		.amdhsa_private_segment_fixed_size 0
		.amdhsa_kernarg_size 424
		.amdhsa_user_sgpr_count 2
		.amdhsa_user_sgpr_dispatch_ptr 0
		.amdhsa_user_sgpr_queue_ptr 0
		.amdhsa_user_sgpr_kernarg_segment_ptr 1
		.amdhsa_user_sgpr_dispatch_id 0
		.amdhsa_user_sgpr_kernarg_preload_length 0
		.amdhsa_user_sgpr_kernarg_preload_offset 0
		.amdhsa_user_sgpr_private_segment_size 0
		.amdhsa_uses_dynamic_stack 0
		.amdhsa_enable_private_segment 0
		.amdhsa_system_sgpr_workgroup_id_x 1
		.amdhsa_system_sgpr_workgroup_id_y 0
		.amdhsa_system_sgpr_workgroup_id_z 0
		.amdhsa_system_sgpr_workgroup_info 0
		.amdhsa_system_vgpr_workitem_id 2
		.amdhsa_next_free_vgpr 243
		.amdhsa_next_free_sgpr 99
		.amdhsa_accum_offset 244
		.amdhsa_reserve_vcc 1
		.amdhsa_float_round_mode_32 0
		.amdhsa_float_round_mode_16_64 0
		.amdhsa_float_denorm_mode_32 3
		.amdhsa_float_denorm_mode_16_64 3
		.amdhsa_dx10_clamp 1
		.amdhsa_ieee_mode 1
		.amdhsa_fp16_overflow 0
		.amdhsa_tg_split 0
		.amdhsa_exception_fp_ieee_invalid_op 0
		.amdhsa_exception_fp_denorm_src 0
		.amdhsa_exception_fp_ieee_div_zero 0
		.amdhsa_exception_fp_ieee_overflow 0
		.amdhsa_exception_fp_ieee_underflow 0
		.amdhsa_exception_fp_ieee_inexact 0
		.amdhsa_exception_int_div_zero 0
	.end_amdhsa_kernel

amdhsa.kernels:
  - .agpr_count:     0
    .args:
      - .offset:         0
        .size:           168
        .value_kind:     by_value
      - .offset:         168
        .size:           4
        .value_kind:     hidden_block_count_x
      - .offset:         172
        .size:           4
        .value_kind:     hidden_block_count_y
      - .offset:         176
        .size:           4
        .value_kind:     hidden_block_count_z
      - .offset:         180
        .size:           2
        .value_kind:     hidden_group_size_x
      - .offset:         182
        .size:           2
        .value_kind:     hidden_group_size_y
      - .offset:         184
        .size:           2
        .value_kind:     hidden_group_size_z
      - .offset:         186
        .size:           2
        .value_kind:     hidden_remainder_x
      - .offset:         188
        .size:           2
        .value_kind:     hidden_remainder_y
      - .offset:         190
        .size:           2
        .value_kind:     hidden_remainder_z
      - .offset:         208
        .size:           8
        .value_kind:     hidden_global_offset_x
      - .offset:         216
        .size:           8
        .value_kind:     hidden_global_offset_y
      - .offset:         224
        .size:           8
        .value_kind:     hidden_global_offset_z
      - .offset:         232
        .size:           2
        .value_kind:     hidden_grid_dims
      - .offset:         256
        .size:           8
        .value_kind:     hidden_multigrid_sync_arg
      - .offset:         288
        .size:           4
        .value_kind:     hidden_dynamic_lds_size
    .group_segment_fixed_size: 0
    .kernarg_segment_align: 8
    .kernarg_segment_size: 424
    .language:       OpenCL C
    .language_version:
      - 2
      - 0
    .max_flat_workgroup_size: 512
    .name:           _Z10fwd_kernel4Args
    .private_segment_fixed_size: 0
    .sgpr_count:     105
    .sgpr_spill_count: 52
    .symbol:         _Z10fwd_kernel4Args.kd
    .uniform_work_group_size: 1
    .uses_dynamic_stack: false
    .vgpr_count:     243
    .vgpr_spill_count: 0
    .wavefront_size: 64
